# P6 conv epilogue rewritten by hand: natural (e,e+1) packed-FMA pairing, conv taps loaded once per column group, no dead v_mov, not rotated across the tile loop
# speedup vs baseline: 1.0229x; 1.0180x over previous
; #define PG8_STAGE(bufoff, gbase, voff) do { _Pragma("unroll") for (int _i = 0; _i < 2; ++_i) \
;         __builtin_amdgcn_global_load_lds((const unsigned*)((const char*)(gbase) + (voff)[_i]), (LAS unsigned*)(lds + (bufoff) + ldsw + _i * 8192), 16, 0, 0); } while (0)
; #define PG8_WAIT_V(n) asm volatile("s_waitcnt vmcnt(" #n ")" ::: "memory")
; #define PG8_BAR __builtin_amdgcn_s_barrier()
;     __device__ bool next(int i, Unit& u) const {
;         const long L = (long)i * G + c; if (L >= nwg) return false;
;         int wgid = (int)L; { const int q = nwg / NXCD, r = nwg % NXCD, xcd = wgid % NXCD, off = wgid / NXCD; wgid = (xcd < r ? xcd * (q + 1) : r * (q + 1) + (xcd - r) * q) + off; }
;         const int nig = WGM * nN, gid = wgid / nig, fm = gid * WGM, gsz = (nM - fm) < WGM ? (nM - fm) : WGM;
;         u.pm = fm + ((wgid % nig) % gsz); u.pn = (wgid % nig) / gsz; return true;
; template <class Epi, bool KS0 = false>
; __device__ __forceinline__ void gemm_phase(const int WID, LAS unsigned char* lds, const Gemm g, const StaticOrder& S, const Epi& E) {
;     ...
;     const char* cA = (const char*)g.A + (size_t)cur.pm * tstep; const char* cB = (const char*)g.Bt + (size_t)cur.pn * tstep;
;     PG8_STAGE(PG8_SB(0, 0), cB, voffB); PG8_STAGE(PG8_SA(0, 0), cA, voffA); PG8_STAGE(PG8_SB(0, 1), cB + hstep, voffB); PG8_STAGE(PG8_SA(0, 1), cA + hstep, voffA);
;     if (wr == 1) PG8_BAR;
;     PG8_WAIT_V(4); PG8_BAR;
;     PG8_STAGE(PG8_SB(1, 0), cB + kstep, voffB); PG8_STAGE(PG8_SA(1, 0), cA + kstep, voffA); PG8_STAGE(PG8_SB(1, 1), cB + hstep + kstep, voffB);
;     PG8_WAIT_V(6); PG8_BAR;
;     for (;;) {
;         const bool has_next = S.next(ui + 1, nxt);
.LBB0_772:
	s_lshl_b32 s14, s81, 9
	s_add_i32 s93, s93, 0x3ffff2
	v_lshlrev_b32_e32 v16, 11, v204
	s_add_u32 s34, s76, 0xb000
	v_add_u32_e32 v16, 0, v16
	s_addc_u32 s35, s77, 0
	s_add_u32 s48, s76, 0x16000
	v_add_u32_e32 v172, 0x1f800, v16
	v_add_u32_e32 v173, 0x20800, v16
	v_and_b32_e32 v16, 15, v14
	s_addc_u32 s49, s77, 0
	s_add_i32 s21, s14, 0
	v_readlane_b32 s14, v251, 39
	v_or_b32_e32 v17, s22, v16
	s_add_i32 s25, s14, 0
	v_lshlrev_b32_e32 v18, 6, v17
	v_and_b32_e32 v19, 48, v14
	s_movk_i32 s14, 0x3c0
	s_mov_b64 s[50:51], 0x80
	v_and_or_b32 v18, v18, s14, v19
	v_and_b32_e32 v15, 0xfffffc00, v15
	v_readlane_b32 s14, v254, 17
	v_lshl_add_u64 v[6:7], v[6:7], 0, s[50:51]
	s_add_i32 m0, s9, 0x18000
	s_add_i32 s21, s21, 0x24000
	s_add_i32 s25, s25, 0x25000
	s_add_i32 s60, s9, 0x22000
	v_add_u32_e32 v20, s14, v15
	v_readlane_b32 s14, v254, 18
	s_waitcnt vmcnt(4)
	s_barrier
	global_load_lds_dwordx4 v[6:7], off
	v_lshl_add_u64 v[4:5], v[4:5], 0, s[50:51]
	s_add_i32 m0, s9, 0x1a000
	s_add_i32 s61, s9, 0x8000
	s_add_i32 s62, s9, 0xa000
	v_add_u32_e32 v15, s14, v15
	global_load_lds_dwordx4 v[4:5], off
	v_lshl_add_u64 v[2:3], v[2:3], 0, s[50:51]
	s_mov_b32 m0, s61
	s_add_u32 s14, s12, 0x80080
	global_load_lds_dwordx4 v[2:3], off
	v_lshl_add_u64 v[0:1], v[0:1], 0, s[50:51]
	s_mov_b32 m0, s62
	s_addc_u32 s15, s13, 0
	global_load_lds_dwordx4 v[0:1], off
	v_lshl_add_u64 v[0:1], s[14:15], 0, v[140:141]
	s_add_i32 m0, s9, 0x1c000
	v_lshlrev_b32_e32 v17, 2, v17
	global_load_lds_dwordx4 v[0:1], off
	v_lshl_add_u64 v[0:1], s[14:15], 0, v[142:143]
	s_add_i32 m0, s9, 0x1e000
	v_lshlrev_b32_e32 v14, 2, v14
	global_load_lds_dwordx4 v[0:1], off
	v_lshlrev_b32_e32 v0, 15, v8
	v_and_b32_e32 v0, 0xffff0000, v0
	v_lshl_add_u32 v0, v9, 12, v0
	v_and_b32_e32 v1, 1, v8
	v_lshl_or_b32 v0, v1, 6, v0
	v_lshl_add_u32 v144, v10, 1, v0
	v_lshlrev_b32_e32 v0, 15, v11
	v_and_b32_e32 v0, 0xffff0000, v0
	v_and_b32_e32 v17, 32, v17
	v_lshl_or_b32 v16, v16, 6, v19
	v_and_b32_e32 v14, 32, v14
	s_waitcnt vmcnt(6)
	v_lshl_add_u32 v0, v12, 12, v0
	v_and_b32_e32 v1, 1, v11
	v_bitop3_b32 v17, v18, v20, v17 bitop3:0xde
	v_bitop3_b32 v174, v16, v15, v14 bitop3:0xde
	v_lshl_or_b32 v0, v1, 6, v0
	s_add_i32 s63, 0, 0x10000
	s_add_i32 s64, 0, 0x14000
	v_mov_b32_e32 v145, v141
	v_lshl_add_u32 v146, v13, 1, v0
	v_mov_b32_e32 v147, v141
	v_mov_b64_e32 v[148:149], 0xb00
	v_mov_b64_e32 v[150:151], 0xaff
	v_add_u32_e32 v175, s63, v174
	v_add_u32_e32 v176, 0, v17
	v_add_u32_e32 v177, s64, v174
	v_mov_b32_e32 v178, 0x358637bd
	s_mov_b32 s65, 0x800000
	s_add_i32 s66, 0, 0x20000
	s_add_i32 s67, 0, 0x21000
	s_mov_b32 s68, 0xb000
	s_movk_i32 s69, 0x2c00
	s_barrier
	s_branch .LBB0_774
.LBB0_774:
	s_add_i32 s20, s20, 1
	s_mul_i32 s14, s20, s97
	s_mul_hi_u32 s15, s20, s96
	s_add_i32 s15, s15, s14
	s_mul_i32 s14, s20, s96
	s_add_u32 s14, s14, s33
	s_addc_u32 s15, s15, s72
	v_cmp_gt_i64_e64 s[40:41], s[14:15], v[150:151]
	s_and_b64 vcc, exec, s[40:41]
	s_cbranch_vccnz .LBB0_776
	s_ashr_i32 s28, s14, 31
	s_lshr_b32 s28, s28, 29
	s_add_i32 s28, s14, s28
	s_ashr_i32 s29, s28, 3
	s_and_b32 s28, s28, -8
	s_sub_i32 s28, s14, s28
	s_cmp_lt_i32 s28, 0
	s_movk_i32 s42, 0x161
	s_cselect_b32 s42, s42, 0x160
	s_mul_i32 s28, s28, s42
	s_add_i32 s28, s28, s29
	s_mul_hi_i32 s29, s28, 0x2e8ba2e9
	s_lshr_b32 s42, s29, 31
	s_ashr_i32 s29, s29, 6
	s_add_i32 s29, s29, s42
	s_lshl_b32 s42, s29, 3
	s_sub_i32 s43, 64, s42
	s_min_i32 s43, s43, 8
	s_abs_i32 s44, s43
	v_cvt_f32_u32_e32 v0, s44
	s_sub_i32 s52, 0, s44
	s_mulk_i32 s29, 0x160
	s_sub_i32 s28, s28, s29
	v_rcp_iflag_f32_e32 v0, v0
	s_abs_i32 s29, s28
	s_xor_b32 s45, s28, s43
	s_ashr_i32 s45, s45, 31
	v_mul_f32_e32 v0, 0x4f7ffffe, v0
	v_cvt_u32_f32_e32 v0, v0
	s_nop 0
	v_readfirstlane_b32 s53, v0
	s_mul_i32 s52, s52, s53
	s_mul_hi_u32 s52, s53, s52
	s_add_i32 s53, s53, s52
	s_mul_hi_u32 s52, s29, s53
	s_mul_i32 s53, s52, s44
	s_sub_i32 s29, s29, s53
	s_add_i32 s54, s52, 1
	s_sub_i32 s53, s29, s44
	s_cmp_ge_u32 s29, s44
	s_cselect_b32 s52, s54, s52
	s_cselect_b32 s29, s53, s29
	s_add_i32 s53, s52, 1
	s_cmp_ge_u32 s29, s44
	s_cselect_b32 s29, s53, s52
	s_xor_b32 s29, s29, s45
	s_sub_i32 s52, s29, s45
	s_mul_i32 s29, s52, s43
	s_sub_i32 s28, s28, s29
	s_add_i32 s54, s42, s28

; #define LAS __attribute__((address_space(3)))
;     __device__ __forceinline__ void operator()(f32x4 (&acc)[2][2][4][2], const Unit& u, int wr, int wc, int fr, int fq) const {
;     ...
; #pragma unroll
;             for (int ai = 0; ai < 2; ++ai)
; #pragma unroll
;                 for (int m = 0; m < 4; ++m) { const float rstd = myr[(ai * 4 + m) * 16 + fr];
; #pragma unroll
;                     for (int bj = 0; bj < 2; ++bj)
; #pragma unroll
;                         for (int n = 0; n < 2; ++n) acc[ai][bj][m][n] *= rstd; }
;         }
;         if (fr >= 14) {
; #pragma unroll
;             for (int ai = 0; ai < 2; ++ai)
; #pragma unroll
;                 for (int bj = 0; bj < 2; ++bj)
; #pragma unroll
;                     for (int n = 0; n < 2; ++n) *(LAS f32x4*)(ex + (((ai * 2 + wr) * 2 + (fr - 14)) * 256 + bj * HALF + cl0 + n * 16)) = acc[ai][bj][3][n];
;         }
;         if (wr == 0 && fr < 2) {
; #pragma unroll
;             for (int bj = 0; bj < 2; ++bj)
; #pragma unroll
;                 for (int n = 0; n < 2; ++n) *(f32x4*)(uedge + ((size_t)(u.pm * 4 + fr) * FF2 + u.pn * BM + bj * HALF + cl0 + n * 16)) = acc[0][bj][0][n];
;         }
;         if (wr == 1 && fr >= 14) {
; #pragma unroll
;             for (int bj = 0; bj < 2; ++bj)
; #pragma unroll
;                 for (int n = 0; n < 2; ++n) *(f32x4*)(uedge + ((size_t)(u.pm * 4 + 2 + (fr - 14)) * FF2 + u.pn * BM + bj * HALF + cl0 + n * 16)) = acc[1][bj][3][n];
.LBB0_798:
	ds_read2_b32 v[180:181], v155 offset1:16
	ds_read2_b32 v[182:183], v155 offset0:32 offset1:48
	ds_read2_b32 v[184:185], v155 offset0:64 offset1:80
	ds_read2_b32 v[186:187], v155 offset0:96 offset1:112
	v_readlane_b32 s2, v254, 19
	v_lshlrev_b32_e32 v153, 2, v132
	s_lshl_b32 s14, s8, 10
	s_lshl_b32 s15, s8, 8
	s_waitcnt lgkmcnt(0)
	v_add_u32_e32 v154, s2, v153
	v_pk_mul_f32 v[88:89], v[88:89], v[182:183] op_sel:[0,1] op_sel_hi:[1,1]
	v_pk_mul_f32 v[90:91], v[90:91], v[182:183] op_sel:[0,1] op_sel_hi:[1,1]
	v_pk_mul_f32 v[24:25], v[24:25], v[182:183] op_sel:[0,1] op_sel_hi:[1,1]
	v_pk_mul_f32 v[26:27], v[26:27], v[182:183] op_sel:[0,1] op_sel_hi:[1,1]
	v_pk_mul_f32 v[28:29], v[28:29], v[182:183] op_sel:[0,1] op_sel_hi:[1,1]
	v_pk_mul_f32 v[30:31], v[30:31], v[182:183] op_sel:[0,1] op_sel_hi:[1,1]
	v_pk_mul_f32 v[20:21], v[20:21], v[182:183] op_sel:[0,1] op_sel_hi:[1,1]
	v_pk_mul_f32 v[22:23], v[22:23], v[182:183] op_sel:[0,1] op_sel_hi:[1,1]
	v_pk_mul_f32 v[16:17], v[16:17], v[186:187] op_sel:[0,1] op_sel_hi:[1,1]
	v_pk_mul_f32 v[18:19], v[18:19], v[186:187] op_sel:[0,1] op_sel_hi:[1,1]
	v_pk_mul_f32 v[8:9], v[8:9], v[186:187] op_sel:[0,1] op_sel_hi:[1,1]
	v_pk_mul_f32 v[10:11], v[10:11], v[186:187] op_sel:[0,1] op_sel_hi:[1,1]
	v_pk_mul_f32 v[4:5], v[4:5], v[186:187] op_sel:[0,1] op_sel_hi:[1,1]
	v_pk_mul_f32 v[6:7], v[6:7], v[186:187] op_sel:[0,1] op_sel_hi:[1,1]
	v_pk_mul_f32 v[0:1], v[0:1], v[186:187] op_sel:[0,1] op_sel_hi:[1,1]
	v_pk_mul_f32 v[2:3], v[2:3], v[186:187] op_sel:[0,1] op_sel_hi:[1,1]
	v_pk_mul_f32 v[128:129], v[128:129], v[180:181] op_sel_hi:[1,0]
	v_pk_mul_f32 v[130:131], v[130:131], v[180:181] op_sel_hi:[1,0]
	v_pk_mul_f32 v[124:125], v[124:125], v[180:181] op_sel_hi:[1,0]
	v_pk_mul_f32 v[126:127], v[126:127], v[180:181] op_sel_hi:[1,0]
	v_pk_mul_f32 v[12:13], v[12:13], v[180:181] op_sel_hi:[1,0]
	v_pk_mul_f32 v[14:15], v[14:15], v[180:181] op_sel_hi:[1,0]
	v_pk_mul_f32 v[120:121], v[120:121], v[180:181] op_sel_hi:[1,0]
	v_pk_mul_f32 v[122:123], v[122:123], v[180:181] op_sel_hi:[1,0]
	v_pk_mul_f32 v[76:77], v[76:77], v[184:185] op_sel_hi:[1,0]
	v_pk_mul_f32 v[78:79], v[78:79], v[184:185] op_sel_hi:[1,0]
	v_pk_mul_f32 v[72:73], v[72:73], v[184:185] op_sel_hi:[1,0]
	v_pk_mul_f32 v[74:75], v[74:75], v[184:185] op_sel_hi:[1,0]
	v_pk_mul_f32 v[60:61], v[60:61], v[184:185] op_sel_hi:[1,0]
	v_pk_mul_f32 v[62:63], v[62:63], v[184:185] op_sel_hi:[1,0]
	v_pk_mul_f32 v[56:57], v[56:57], v[184:185] op_sel_hi:[1,0]
	v_pk_mul_f32 v[58:59], v[58:59], v[184:185] op_sel_hi:[1,0]
	v_pk_mul_f32 v[116:117], v[116:117], v[180:181] op_sel:[0,1] op_sel_hi:[1,1]
	v_pk_mul_f32 v[118:119], v[118:119], v[180:181] op_sel:[0,1] op_sel_hi:[1,1]
	v_pk_mul_f32 v[112:113], v[112:113], v[180:181] op_sel:[0,1] op_sel_hi:[1,1]
	v_pk_mul_f32 v[114:115], v[114:115], v[180:181] op_sel:[0,1] op_sel_hi:[1,1]
	v_pk_mul_f32 v[100:101], v[100:101], v[180:181] op_sel:[0,1] op_sel_hi:[1,1]
	v_pk_mul_f32 v[102:103], v[102:103], v[180:181] op_sel:[0,1] op_sel_hi:[1,1]
	v_pk_mul_f32 v[92:93], v[92:93], v[180:181] op_sel:[0,1] op_sel_hi:[1,1]
	v_pk_mul_f32 v[94:95], v[94:95], v[180:181] op_sel:[0,1] op_sel_hi:[1,1]
	v_pk_mul_f32 v[68:69], v[68:69], v[184:185] op_sel:[0,1] op_sel_hi:[1,1]
	v_pk_mul_f32 v[70:71], v[70:71], v[184:185] op_sel:[0,1] op_sel_hi:[1,1]
	v_pk_mul_f32 v[64:65], v[64:65], v[184:185] op_sel:[0,1] op_sel_hi:[1,1]
	v_pk_mul_f32 v[66:67], v[66:67], v[184:185] op_sel:[0,1] op_sel_hi:[1,1]
	v_pk_mul_f32 v[44:45], v[44:45], v[184:185] op_sel:[0,1] op_sel_hi:[1,1]
	v_pk_mul_f32 v[46:47], v[46:47], v[184:185] op_sel:[0,1] op_sel_hi:[1,1]
	v_pk_mul_f32 v[40:41], v[40:41], v[184:185] op_sel:[0,1] op_sel_hi:[1,1]
	v_pk_mul_f32 v[42:43], v[42:43], v[184:185] op_sel:[0,1] op_sel_hi:[1,1]
	v_pk_mul_f32 v[104:105], v[104:105], v[182:183] op_sel_hi:[1,0]
	v_pk_mul_f32 v[106:107], v[106:107], v[182:183] op_sel_hi:[1,0]
	v_pk_mul_f32 v[96:97], v[96:97], v[182:183] op_sel_hi:[1,0]
	v_pk_mul_f32 v[98:99], v[98:99], v[182:183] op_sel_hi:[1,0]
	v_pk_mul_f32 v[84:85], v[84:85], v[182:183] op_sel_hi:[1,0]
	v_pk_mul_f32 v[86:87], v[86:87], v[182:183] op_sel_hi:[1,0]
	v_pk_mul_f32 v[80:81], v[80:81], v[182:183] op_sel_hi:[1,0]
	v_pk_mul_f32 v[82:83], v[82:83], v[182:183] op_sel_hi:[1,0]
	v_pk_mul_f32 v[52:53], v[52:53], v[186:187] op_sel_hi:[1,0]
	v_pk_mul_f32 v[54:55], v[54:55], v[186:187] op_sel_hi:[1,0]
	v_pk_mul_f32 v[48:49], v[48:49], v[186:187] op_sel_hi:[1,0]
	v_pk_mul_f32 v[50:51], v[50:51], v[186:187] op_sel_hi:[1,0]
	v_pk_mul_f32 v[36:37], v[36:37], v[186:187] op_sel_hi:[1,0]
	v_pk_mul_f32 v[38:39], v[38:39], v[186:187] op_sel_hi:[1,0]
	v_pk_mul_f32 v[32:33], v[32:33], v[186:187] op_sel_hi:[1,0]
	v_pk_mul_f32 v[34:35], v[34:35], v[186:187] op_sel_hi:[1,0]
	v_cmp_lt_i32_e32 vcc, 13, v179
	s_and_saveexec_b64 s[2:3], vcc
	s_cbranch_execz .Lp6_noex
	v_add_lshl_u32 v155, s93, v179, 10
	v_lshl_add_u32 v155, v154, 2, v155
	v_add_u32_e32 v155, s66, v155
	ds_write_b128 v155, v[88:91]
	ds_write_b128 v155, v[24:27] offset:64
	ds_write_b128 v155, v[28:31] offset:512
	ds_write_b128 v155, v[20:23] offset:576
	ds_write_b128 v155, v[16:19] offset:4096
	ds_write_b128 v155, v[8:11] offset:4160
	ds_write_b128 v155, v[4:7] offset:4608
	ds_write_b128 v155, v[0:3] offset:4672
.Lp6_noex:
	s_or_b64 exec, exec, s[2:3]
	s_cmp_lg_u32 s22, 0
	s_cbranch_scc1 .Lp6_ue_wr1
	v_cmp_gt_i32_e32 vcc, 2, v179
	s_and_saveexec_b64 s[2:3], vcc
	s_cbranch_execz .Lp6_ue_done
	v_lshl_add_u32 v155, s10, 2, v179
	v_mul_lo_u32 v155, v155, s68
	v_lshl_add_u32 v155, v154, 2, v155
	v_add_u32_e32 v155, s14, v155
	global_store_dwordx4 v155, v[128:131], s[30:31]
	global_store_dwordx4 v155, v[124:127], s[30:31] offset:64
	global_store_dwordx4 v155, v[12:15], s[30:31] offset:512
	global_store_dwordx4 v155, v[120:123], s[30:31] offset:576
	s_branch .Lp6_ue_done
; #define LAS __attribute__((address_space(3)))
; __device__ __forceinline__ float dpp_ror1(float v) { return __int_as_float(__builtin_amdgcn_update_dpp(0, __float_as_int(v), 0x121, 0xf, 0xf, false)); }
;     __device__ __forceinline__ void conv_rows(const f32x4 curg, const f32x4 curv, f32x4 (&q1)[2], f32x4 (&q2)[2], const LAS float* cp, bf16_t* dst, const bool upd) const {
;         f32x4 uc[2];
; #pragma unroll
;         for (int bj = 0; bj < 2; ++bj) {
;             const f32x4 c0 = *(const LAS f32x4*)(cp + bj * 32), c1 = *(const LAS f32x4*)(cp + bj * 32 + 64), c2 = *(const LAS f32x4*)(cp + bj * 32 + 128), bb = *(const LAS f32x4*)(cp + bj * 32 + 192);
;             const f32x4 cur = bj ? curv : curg;
; #pragma unroll
;             for (int e = 0; e < 4; ++e) {
;                 const float p1 = dpp_shr1(q1[bj][e], cur[e]), p2 = dpp_shr2(q2[bj][e], cur[e]);
;                 uc[bj][e] = bb[e] + c0[e] * p2 + c1[e] * p1 + c2[e] * cur[e];
;                 if (upd) { q1[bj][e] = dpp_ror1(cur[e]); q2[bj][e] = dpp_ror2(cur[e]); }
;     __device__ __forceinline__ void operator()(f32x4 (&acc)[2][2][4][2], const Unit& u, int wr, int wc, int fr, int fq) const {
;     ...
;         if (wr == 1 && fr >= 14) {
; #pragma unroll
;             for (int bj = 0; bj < 2; ++bj)
; #pragma unroll
;                 for (int n = 0; n < 2; ++n) *(f32x4*)(uedge + ((size_t)(u.pm * 4 + 2 + (fr - 14)) * FF2 + u.pn * BM + bj * HALF + cl0 + n * 16)) = acc[1][bj][3][n];
;         }
;         LAS float* myc = cws + wv * 256;
; #pragma unroll
;         for (int i = 0; i < 4; ++i) myc[i * 64 + ln] = cwr[i];
;         asm volatile("s_waitcnt lgkmcnt(0)" ::: "memory");
; #pragma unroll
;         for (int n = 0; n < 2; ++n) {
;             const int jcol = u.pn * HALF + cl0 + n * 16; const LAS float* cp = myc + 16 * n + 4 * fq;
; #pragma unroll
;             for (int ai = 0; ai < 2; ++ai) {
;                 f32x4 q1[2], q2[2];
; #pragma unroll
;                 for (int bj = 0; bj < 2; ++bj)
; #pragma unroll
;                     for (int e = 0; e < 4; ++e) { q1[bj][e] = dpp_ror1(acc[ai][bj][0][n][e]); q2[bj][e] = dpp_ror2(acc[ai][bj][0][n][e]); }
; #pragma unroll
;                 for (int m = 1; m < 4; ++m) conv_rows(acc[ai][0][m][n], acc[ai][1][m][n], q1, q2, cp, act + (size_t)(rowt + ai * HALF + m * 16) * FF + jcol, m < 3);
.Lp6_ue_wr1:
	v_cmp_lt_i32_e32 vcc, 13, v179
	s_and_saveexec_b64 s[2:3], vcc
	s_cbranch_execz .Lp6_ue_done
	v_lshl_add_u32 v155, s10, 2, v179
	v_add_u32_e32 v155, -12, v155
	v_mul_lo_u32 v155, v155, s68
	v_lshl_add_u32 v155, v154, 2, v155
	v_add_u32_e32 v155, s14, v155
	global_store_dwordx4 v155, v[16:19], s[30:31]
	global_store_dwordx4 v155, v[8:11], s[30:31] offset:64
	global_store_dwordx4 v155, v[4:7], s[30:31] offset:512
	global_store_dwordx4 v155, v[0:3], s[30:31] offset:576
.Lp6_ue_done:
	s_or_b64 exec, exec, s[2:3]
	v_lshl_add_u32 v155, v164, 2, s60
	s_waitcnt vmcnt(0)
	ds_write2st64_b32 v155, v165, v166 offset1:1
	ds_write2st64_b32 v155, v167, v168 offset0:2 offset1:3
	v_lshl_add_u32 v153, v153, 2, s60
	v_mul_lo_u32 v155, v152, s69
	v_lshl_add_u32 v155, v154, 1, v155
	v_add_u32_e32 v155, s15, v155
	v_cmp_eq_u32_e64 s[42:43], 1, v179
	s_waitcnt lgkmcnt(0)
	ds_read_b128 v[188:191], v153
	ds_read_b128 v[192:195], v153 offset:128
	ds_read_b128 v[196:199], v153 offset:256
	ds_read_b128 v[200:203], v153 offset:384
	ds_read_b128 v[204:207], v153 offset:512
	ds_read_b128 v[210:213], v153 offset:640
	ds_read_b128 v[214:217], v153 offset:768
	ds_read_b128 v[218:221], v153 offset:896
	v_mov_b32_dpp v222, v128 row_ror:1 row_mask:0xf bank_mask:0xf
	v_mov_b32_dpp v223, v129 row_ror:1 row_mask:0xf bank_mask:0xf
	v_mov_b32_dpp v224, v130 row_ror:1 row_mask:0xf bank_mask:0xf
	v_mov_b32_dpp v225, v131 row_ror:1 row_mask:0xf bank_mask:0xf
	v_mov_b32_dpp v230, v128 row_ror:2 row_mask:0xf bank_mask:0xf
	v_mov_b32_dpp v231, v129 row_ror:2 row_mask:0xf bank_mask:0xf
	v_mov_b32_dpp v232, v130 row_ror:2 row_mask:0xf bank_mask:0xf
	v_mov_b32_dpp v233, v131 row_ror:2 row_mask:0xf bank_mask:0xf
	v_mov_b32_dpp v226, v12 row_ror:1 row_mask:0xf bank_mask:0xf
	v_mov_b32_dpp v227, v13 row_ror:1 row_mask:0xf bank_mask:0xf
	v_mov_b32_dpp v228, v14 row_ror:1 row_mask:0xf bank_mask:0xf
	v_mov_b32_dpp v229, v15 row_ror:1 row_mask:0xf bank_mask:0xf
	v_mov_b32_dpp v108, v12 row_ror:2 row_mask:0xf bank_mask:0xf
	v_mov_b32_dpp v109, v13 row_ror:2 row_mask:0xf bank_mask:0xf
	v_mov_b32_dpp v110, v14 row_ror:2 row_mask:0xf bank_mask:0xf
	v_mov_b32_dpp v111, v15 row_ror:2 row_mask:0xf bank_mask:0xf
	s_waitcnt lgkmcnt(0)
	v_mov_b32_dpp v222, v116 row_shr:1 row_mask:0xf bank_mask:0xf
	v_mov_b32_dpp v223, v117 row_shr:1 row_mask:0xf bank_mask:0xf
	v_mov_b32_dpp v224, v118 row_shr:1 row_mask:0xf bank_mask:0xf
	v_mov_b32_dpp v225, v119 row_shr:1 row_mask:0xf bank_mask:0xf
	v_mov_b32_dpp v230, v116 row_shr:2 row_mask:0xf bank_mask:0xf
	v_mov_b32_dpp v231, v117 row_shr:2 row_mask:0xf bank_mask:0xf
	v_mov_b32_dpp v232, v118 row_shr:2 row_mask:0xf bank_mask:0xf
	v_mov_b32_dpp v233, v119 row_shr:2 row_mask:0xf bank_mask:0xf
	v_mov_b32_dpp v226, v100 row_shr:1 row_mask:0xf bank_mask:0xf
	v_mov_b32_dpp v227, v101 row_shr:1 row_mask:0xf bank_mask:0xf
	v_mov_b32_dpp v228, v102 row_shr:1 row_mask:0xf bank_mask:0xf
	v_mov_b32_dpp v229, v103 row_shr:1 row_mask:0xf bank_mask:0xf
	v_mov_b32_dpp v108, v100 row_shr:2 row_mask:0xf bank_mask:0xf
	v_mov_b32_dpp v109, v101 row_shr:2 row_mask:0xf bank_mask:0xf
	v_mov_b32_dpp v110, v102 row_shr:2 row_mask:0xf bank_mask:0xf
	v_mov_b32_dpp v111, v103 row_shr:2 row_mask:0xf bank_mask:0xf
	v_mov_b32_dpp v132, v116 row_ror:1 row_mask:0xf bank_mask:0xf
	v_mov_b32_dpp v133, v117 row_ror:1 row_mask:0xf bank_mask:0xf
	v_mov_b32_dpp v134, v118 row_ror:1 row_mask:0xf bank_mask:0xf
	v_mov_b32_dpp v135, v119 row_ror:1 row_mask:0xf bank_mask:0xf
	v_mov_b32_dpp v156, v116 row_ror:2 row_mask:0xf bank_mask:0xf
	v_mov_b32_dpp v157, v117 row_ror:2 row_mask:0xf bank_mask:0xf
	v_mov_b32_dpp v158, v118 row_ror:2 row_mask:0xf bank_mask:0xf
	v_mov_b32_dpp v159, v119 row_ror:2 row_mask:0xf bank_mask:0xf
	v_mov_b32_dpp v136, v100 row_ror:1 row_mask:0xf bank_mask:0xf
	v_mov_b32_dpp v137, v101 row_ror:1 row_mask:0xf bank_mask:0xf
	v_mov_b32_dpp v138, v102 row_ror:1 row_mask:0xf bank_mask:0xf
	v_mov_b32_dpp v139, v103 row_ror:1 row_mask:0xf bank_mask:0xf
	v_mov_b32_dpp v160, v100 row_ror:2 row_mask:0xf bank_mask:0xf
	v_mov_b32_dpp v161, v101 row_ror:2 row_mask:0xf bank_mask:0xf
	v_mov_b32_dpp v162, v102 row_ror:2 row_mask:0xf bank_mask:0xf
	v_mov_b32_dpp v163, v103 row_ror:2 row_mask:0xf bank_mask:0xf
	v_pk_fma_f32 v[164:165], v[188:189], v[230:231], v[214:215]
	v_pk_fma_f32 v[166:167], v[190:191], v[232:233], v[216:217]
	v_pk_fma_f32 v[164:165], v[196:197], v[222:223], v[164:165]
	v_pk_fma_f32 v[166:167], v[198:199], v[224:225], v[166:167]
	v_pk_fma_f32 v[164:165], v[116:117], v[204:205], v[164:165]
	v_pk_fma_f32 v[166:167], v[118:119], v[206:207], v[166:167]
	v_pk_fma_f32 v[168:169], v[192:193], v[108:109], v[218:219]
	v_pk_fma_f32 v[170:171], v[194:195], v[110:111], v[220:221]
	v_pk_fma_f32 v[168:169], v[200:201], v[226:227], v[168:169]
	v_pk_fma_f32 v[170:171], v[202:203], v[228:229], v[170:171]
	v_pk_fma_f32 v[168:169], v[100:101], v[210:211], v[168:169]
	v_pk_fma_f32 v[170:171], v[102:103], v[212:213], v[170:171]
	v_mul_f32_e32 v222, 0xbfb8aa3b, v164
	v_mul_f32_e32 v223, 0xbfb8aa3b, v165
	v_mul_f32_e32 v224, 0xbfb8aa3b, v166
	v_mul_f32_e32 v225, 0xbfb8aa3b, v167
	v_exp_f32_e32 v222, v222
	v_exp_f32_e32 v223, v223
	v_exp_f32_e32 v224, v224
	v_exp_f32_e32 v225, v225
	v_add_f32_e32 v222, 1.0, v222
	v_add_f32_e32 v223, 1.0, v223
	v_add_f32_e32 v224, 1.0, v224
	v_add_f32_e32 v225, 1.0, v225
	v_rcp_f32_e32 v222, v222
	v_rcp_f32_e32 v223, v223
	v_rcp_f32_e32 v224, v224
	v_rcp_f32_e32 v225, v225
	v_mul_f32_e32 v164, v164, v222
	v_mul_f32_e32 v165, v165, v223
	v_mul_f32_e32 v166, v166, v224
	v_mul_f32_e32 v167, v167, v225
	v_mul_f32_e32 v164, v164, v168
	v_mul_f32_e32 v165, v165, v169
; #define LAS __attribute__((address_space(3)))
; __device__ __forceinline__ unsigned cvt_pk_bf16(float lo, float hi) { unsigned r; asm volatile("v_cvt_pk_bf16_f32 %0, %1, %2" : "=v"(r) : "v"(lo), "v"(hi)); return r; }
; __device__ __forceinline__ float sigmoidf_(float x) { return __builtin_amdgcn_rcpf(1.0f + __expf(-x)); }
; __device__ __forceinline__ float dpp_ror1(float v) { return __int_as_float(__builtin_amdgcn_update_dpp(0, __float_as_int(v), 0x121, 0xf, 0xf, false)); }
; __device__ __forceinline__ float dpp_shr1(float old, float v) { return __int_as_float(__builtin_amdgcn_update_dpp(__float_as_int(old), __float_as_int(v), 0x111, 0xf, 0xf, false)); }
;     __device__ __forceinline__ void conv_rows(const f32x4 curg, const f32x4 curv, f32x4 (&q1)[2], f32x4 (&q2)[2], const LAS float* cp, bf16_t* dst, const bool upd) const {
;         f32x4 uc[2];
; #pragma unroll
;         for (int bj = 0; bj < 2; ++bj) {
;             const f32x4 c0 = *(const LAS f32x4*)(cp + bj * 32), c1 = *(const LAS f32x4*)(cp + bj * 32 + 64), c2 = *(const LAS f32x4*)(cp + bj * 32 + 128), bb = *(const LAS f32x4*)(cp + bj * 32 + 192);
;             const f32x4 cur = bj ? curv : curg;
; #pragma unroll
;             for (int e = 0; e < 4; ++e) {
;                 const float p1 = dpp_shr1(q1[bj][e], cur[e]), p2 = dpp_shr2(q2[bj][e], cur[e]);
;                 uc[bj][e] = bb[e] + c0[e] * p2 + c1[e] * p1 + c2[e] * cur[e];
;                 if (upd) { q1[bj][e] = dpp_ror1(cur[e]); q2[bj][e] = dpp_ror2(cur[e]); }
;             }
;         }
;         u32x2 w;
;         { const float a0 = uc[0][0] * sigmoidf_(uc[0][0]) * uc[1][0], a1 = uc[0][1] * sigmoidf_(uc[0][1]) * uc[1][1];
;           const float a2 = uc[0][2] * sigmoidf_(uc[0][2]) * uc[1][2], a3 = uc[0][3] * sigmoidf_(uc[0][3]) * uc[1][3];
;           w.x = cvt_pk_bf16(a0, a1); w.y = cvt_pk_bf16(a2, a3); }
;         *(u32x2*)dst = w;
;     __device__ __forceinline__ void operator()(f32x4 (&acc)[2][2][4][2], const Unit& u, int wr, int wc, int fr, int fq) const {
;     ...
;                     for (int e = 0; e < 4; ++e) { q1[bj][e] = dpp_ror1(acc[ai][bj][0][n][e]); q2[bj][e] = dpp_ror2(acc[ai][bj][0][n][e]); }
; #pragma unroll
;                 for (int m = 1; m < 4; ++m) conv_rows(acc[ai][0][m][n], acc[ai][1][m][n], q1, q2, cp, act + (size_t)(rowt + ai * HALF + m * 16) * FF + jcol, m < 3);
	v_mul_f32_e32 v166, v166, v170
	v_mul_f32_e32 v167, v167, v171
	v_cvt_pk_bf16_f32 v164, v164, v165
	v_cvt_pk_bf16_f32 v165, v166, v167
	v_add_u32_e32 v181, 0x2c000, v155
	global_store_dwordx2 v181, v[164:165], s[0:1]
	v_mov_b32_dpp v132, v104 row_shr:1 row_mask:0xf bank_mask:0xf
	v_mov_b32_dpp v133, v105 row_shr:1 row_mask:0xf bank_mask:0xf
	v_mov_b32_dpp v134, v106 row_shr:1 row_mask:0xf bank_mask:0xf
	v_mov_b32_dpp v135, v107 row_shr:1 row_mask:0xf bank_mask:0xf
	v_mov_b32_dpp v156, v104 row_shr:2 row_mask:0xf bank_mask:0xf
	v_mov_b32_dpp v157, v105 row_shr:2 row_mask:0xf bank_mask:0xf
	v_mov_b32_dpp v158, v106 row_shr:2 row_mask:0xf bank_mask:0xf
	v_mov_b32_dpp v159, v107 row_shr:2 row_mask:0xf bank_mask:0xf
	v_mov_b32_dpp v136, v84 row_shr:1 row_mask:0xf bank_mask:0xf
	v_mov_b32_dpp v137, v85 row_shr:1 row_mask:0xf bank_mask:0xf
	v_mov_b32_dpp v138, v86 row_shr:1 row_mask:0xf bank_mask:0xf
	v_mov_b32_dpp v139, v87 row_shr:1 row_mask:0xf bank_mask:0xf
	v_mov_b32_dpp v160, v84 row_shr:2 row_mask:0xf bank_mask:0xf
	v_mov_b32_dpp v161, v85 row_shr:2 row_mask:0xf bank_mask:0xf
	v_mov_b32_dpp v162, v86 row_shr:2 row_mask:0xf bank_mask:0xf
	v_mov_b32_dpp v163, v87 row_shr:2 row_mask:0xf bank_mask:0xf
	v_mov_b32_dpp v222, v104 row_ror:1 row_mask:0xf bank_mask:0xf
	v_mov_b32_dpp v223, v105 row_ror:1 row_mask:0xf bank_mask:0xf
	v_mov_b32_dpp v224, v106 row_ror:1 row_mask:0xf bank_mask:0xf
	v_mov_b32_dpp v225, v107 row_ror:1 row_mask:0xf bank_mask:0xf
	v_mov_b32_dpp v230, v104 row_ror:2 row_mask:0xf bank_mask:0xf
	v_mov_b32_dpp v231, v105 row_ror:2 row_mask:0xf bank_mask:0xf
	v_mov_b32_dpp v232, v106 row_ror:2 row_mask:0xf bank_mask:0xf
	v_mov_b32_dpp v233, v107 row_ror:2 row_mask:0xf bank_mask:0xf
	v_mov_b32_dpp v226, v84 row_ror:1 row_mask:0xf bank_mask:0xf
	v_mov_b32_dpp v227, v85 row_ror:1 row_mask:0xf bank_mask:0xf
	v_mov_b32_dpp v228, v86 row_ror:1 row_mask:0xf bank_mask:0xf
	v_mov_b32_dpp v229, v87 row_ror:1 row_mask:0xf bank_mask:0xf
	v_mov_b32_dpp v108, v84 row_ror:2 row_mask:0xf bank_mask:0xf
	v_mov_b32_dpp v109, v85 row_ror:2 row_mask:0xf bank_mask:0xf
	v_mov_b32_dpp v110, v86 row_ror:2 row_mask:0xf bank_mask:0xf
	v_mov_b32_dpp v111, v87 row_ror:2 row_mask:0xf bank_mask:0xf
	v_pk_fma_f32 v[164:165], v[188:189], v[156:157], v[214:215]
	v_pk_fma_f32 v[166:167], v[190:191], v[158:159], v[216:217]
	v_pk_fma_f32 v[164:165], v[196:197], v[132:133], v[164:165]
	v_pk_fma_f32 v[166:167], v[198:199], v[134:135], v[166:167]
	v_pk_fma_f32 v[164:165], v[104:105], v[204:205], v[164:165]
	v_pk_fma_f32 v[166:167], v[106:107], v[206:207], v[166:167]
	v_pk_fma_f32 v[168:169], v[192:193], v[160:161], v[218:219]
	v_pk_fma_f32 v[170:171], v[194:195], v[162:163], v[220:221]
	v_pk_fma_f32 v[168:169], v[200:201], v[136:137], v[168:169]
	v_pk_fma_f32 v[170:171], v[202:203], v[138:139], v[170:171]
	v_pk_fma_f32 v[168:169], v[84:85], v[210:211], v[168:169]
	v_pk_fma_f32 v[170:171], v[86:87], v[212:213], v[170:171]
	v_mul_f32_e32 v132, 0xbfb8aa3b, v164
	v_mul_f32_e32 v133, 0xbfb8aa3b, v165
	v_mul_f32_e32 v134, 0xbfb8aa3b, v166
	v_mul_f32_e32 v135, 0xbfb8aa3b, v167
	v_exp_f32_e32 v132, v132
	v_exp_f32_e32 v133, v133
	v_exp_f32_e32 v134, v134
	v_exp_f32_e32 v135, v135
	v_add_f32_e32 v132, 1.0, v132
	v_add_f32_e32 v133, 1.0, v133
	v_add_f32_e32 v134, 1.0, v134
	v_add_f32_e32 v135, 1.0, v135
	v_rcp_f32_e32 v132, v132
	v_rcp_f32_e32 v133, v133
	v_rcp_f32_e32 v134, v134
	v_rcp_f32_e32 v135, v135
	v_mul_f32_e32 v164, v164, v132
	v_mul_f32_e32 v165, v165, v133
	v_mul_f32_e32 v166, v166, v134
	v_mul_f32_e32 v167, v167, v135
	v_mul_f32_e32 v164, v164, v168
	v_mul_f32_e32 v165, v165, v169
	v_mul_f32_e32 v166, v166, v170
	v_mul_f32_e32 v167, v167, v171
	v_cvt_pk_bf16_f32 v164, v164, v165
	v_cvt_pk_bf16_f32 v165, v166, v167
	v_add_u32_e32 v181, 0x58000, v155
	global_store_dwordx2 v181, v[164:165], s[0:1]
	v_mov_b32_dpp v222, v88 row_shr:1 row_mask:0xf bank_mask:0xf
	v_mov_b32_dpp v223, v89 row_shr:1 row_mask:0xf bank_mask:0xf
	v_mov_b32_dpp v224, v90 row_shr:1 row_mask:0xf bank_mask:0xf
	v_mov_b32_dpp v225, v91 row_shr:1 row_mask:0xf bank_mask:0xf
	v_mov_b32_dpp v230, v88 row_shr:2 row_mask:0xf bank_mask:0xf
	v_mov_b32_dpp v231, v89 row_shr:2 row_mask:0xf bank_mask:0xf
	v_mov_b32_dpp v232, v90 row_shr:2 row_mask:0xf bank_mask:0xf
	v_mov_b32_dpp v233, v91 row_shr:2 row_mask:0xf bank_mask:0xf
	v_mov_b32_dpp v226, v28 row_shr:1 row_mask:0xf bank_mask:0xf
	v_mov_b32_dpp v227, v29 row_shr:1 row_mask:0xf bank_mask:0xf
	v_mov_b32_dpp v228, v30 row_shr:1 row_mask:0xf bank_mask:0xf
	v_mov_b32_dpp v229, v31 row_shr:1 row_mask:0xf bank_mask:0xf
	v_mov_b32_dpp v108, v28 row_shr:2 row_mask:0xf bank_mask:0xf
	v_mov_b32_dpp v109, v29 row_shr:2 row_mask:0xf bank_mask:0xf
	v_mov_b32_dpp v110, v30 row_shr:2 row_mask:0xf bank_mask:0xf
	v_mov_b32_dpp v111, v31 row_shr:2 row_mask:0xf bank_mask:0xf
	v_pk_fma_f32 v[164:165], v[188:189], v[230:231], v[214:215]
	v_pk_fma_f32 v[166:167], v[190:191], v[232:233], v[216:217]
	v_pk_fma_f32 v[164:165], v[196:197], v[222:223], v[164:165]
	v_pk_fma_f32 v[166:167], v[198:199], v[224:225], v[166:167]
	v_pk_fma_f32 v[164:165], v[88:89], v[204:205], v[164:165]
	v_pk_fma_f32 v[166:167], v[90:91], v[206:207], v[166:167]
	v_pk_fma_f32 v[168:169], v[192:193], v[108:109], v[218:219]
	v_pk_fma_f32 v[170:171], v[194:195], v[110:111], v[220:221]
	v_pk_fma_f32 v[168:169], v[200:201], v[226:227], v[168:169]
	v_pk_fma_f32 v[170:171], v[202:203], v[228:229], v[170:171]
	v_pk_fma_f32 v[168:169], v[28:29], v[210:211], v[168:169]
	v_pk_fma_f32 v[170:171], v[30:31], v[212:213], v[170:171]
	v_mul_f32_e32 v222, 0xbfb8aa3b, v164
	v_mul_f32_e32 v223, 0xbfb8aa3b, v165
; #define LAS __attribute__((address_space(3)))
; __device__ __forceinline__ unsigned cvt_pk_bf16(float lo, float hi) { unsigned r; asm volatile("v_cvt_pk_bf16_f32 %0, %1, %2" : "=v"(r) : "v"(lo), "v"(hi)); return r; }
; __device__ __forceinline__ float sigmoidf_(float x) { return __builtin_amdgcn_rcpf(1.0f + __expf(-x)); }
; __device__ __forceinline__ float dpp_ror1(float v) { return __int_as_float(__builtin_amdgcn_update_dpp(0, __float_as_int(v), 0x121, 0xf, 0xf, false)); }
;     __device__ __forceinline__ void conv_rows(const f32x4 curg, const f32x4 curv, f32x4 (&q1)[2], f32x4 (&q2)[2], const LAS float* cp, bf16_t* dst, const bool upd) const {
;         f32x4 uc[2];
; #pragma unroll
;         for (int bj = 0; bj < 2; ++bj) {
;             const f32x4 c0 = *(const LAS f32x4*)(cp + bj * 32), c1 = *(const LAS f32x4*)(cp + bj * 32 + 64), c2 = *(const LAS f32x4*)(cp + bj * 32 + 128), bb = *(const LAS f32x4*)(cp + bj * 32 + 192);
;             const f32x4 cur = bj ? curv : curg;
; #pragma unroll
;             for (int e = 0; e < 4; ++e) {
;                 const float p1 = dpp_shr1(q1[bj][e], cur[e]), p2 = dpp_shr2(q2[bj][e], cur[e]);
;                 uc[bj][e] = bb[e] + c0[e] * p2 + c1[e] * p1 + c2[e] * cur[e];
;                 if (upd) { q1[bj][e] = dpp_ror1(cur[e]); q2[bj][e] = dpp_ror2(cur[e]); }
;             }
;         }
;         u32x2 w;
;         { const float a0 = uc[0][0] * sigmoidf_(uc[0][0]) * uc[1][0], a1 = uc[0][1] * sigmoidf_(uc[0][1]) * uc[1][1];
;           const float a2 = uc[0][2] * sigmoidf_(uc[0][2]) * uc[1][2], a3 = uc[0][3] * sigmoidf_(uc[0][3]) * uc[1][3];
;           w.x = cvt_pk_bf16(a0, a1); w.y = cvt_pk_bf16(a2, a3); }
;         *(u32x2*)dst = w;
;     __device__ __forceinline__ void operator()(f32x4 (&acc)[2][2][4][2], const Unit& u, int wr, int wc, int fr, int fq) const {
;     ...
;             for (int ai = 0; ai < 2; ++ai) {
;                 f32x4 q1[2], q2[2];
; #pragma unroll
;                 for (int bj = 0; bj < 2; ++bj)
; #pragma unroll
;                     for (int e = 0; e < 4; ++e) { q1[bj][e] = dpp_ror1(acc[ai][bj][0][n][e]); q2[bj][e] = dpp_ror2(acc[ai][bj][0][n][e]); }
; #pragma unroll
;                 for (int m = 1; m < 4; ++m) conv_rows(acc[ai][0][m][n], acc[ai][1][m][n], q1, q2, cp, act + (size_t)(rowt + ai * HALF + m * 16) * FF + jcol, m < 3);
	v_mul_f32_e32 v224, 0xbfb8aa3b, v166
	v_mul_f32_e32 v225, 0xbfb8aa3b, v167
	v_exp_f32_e32 v222, v222
	v_exp_f32_e32 v223, v223
	v_exp_f32_e32 v224, v224
	v_exp_f32_e32 v225, v225
	v_add_f32_e32 v222, 1.0, v222
	v_add_f32_e32 v223, 1.0, v223
	v_add_f32_e32 v224, 1.0, v224
	v_add_f32_e32 v225, 1.0, v225
	v_rcp_f32_e32 v222, v222
	v_rcp_f32_e32 v223, v223
	v_rcp_f32_e32 v224, v224
	v_rcp_f32_e32 v225, v225
	v_mul_f32_e32 v164, v164, v222
	v_mul_f32_e32 v165, v165, v223
	v_mul_f32_e32 v166, v166, v224
	v_mul_f32_e32 v167, v167, v225
	v_mul_f32_e32 v164, v164, v168
	v_mul_f32_e32 v165, v165, v169
	v_mul_f32_e32 v166, v166, v170
	v_mul_f32_e32 v167, v167, v171
	v_cvt_pk_bf16_f32 v164, v164, v165
	v_cvt_pk_bf16_f32 v165, v166, v167
	v_add_u32_e32 v181, 0x84000, v155
	global_store_dwordx2 v181, v[164:165], s[0:1]
	v_mov_b32_dpp v222, v76 row_ror:1 row_mask:0xf bank_mask:0xf
	v_mov_b32_dpp v223, v77 row_ror:1 row_mask:0xf bank_mask:0xf
	v_mov_b32_dpp v224, v78 row_ror:1 row_mask:0xf bank_mask:0xf
	v_mov_b32_dpp v225, v79 row_ror:1 row_mask:0xf bank_mask:0xf
	v_mov_b32_dpp v230, v76 row_ror:2 row_mask:0xf bank_mask:0xf
	v_mov_b32_dpp v231, v77 row_ror:2 row_mask:0xf bank_mask:0xf
	v_mov_b32_dpp v232, v78 row_ror:2 row_mask:0xf bank_mask:0xf
	v_mov_b32_dpp v233, v79 row_ror:2 row_mask:0xf bank_mask:0xf
	v_mov_b32_dpp v226, v60 row_ror:1 row_mask:0xf bank_mask:0xf
	v_mov_b32_dpp v227, v61 row_ror:1 row_mask:0xf bank_mask:0xf
	v_mov_b32_dpp v228, v62 row_ror:1 row_mask:0xf bank_mask:0xf
	v_mov_b32_dpp v229, v63 row_ror:1 row_mask:0xf bank_mask:0xf
	v_mov_b32_dpp v108, v60 row_ror:2 row_mask:0xf bank_mask:0xf
	v_mov_b32_dpp v109, v61 row_ror:2 row_mask:0xf bank_mask:0xf
	v_mov_b32_dpp v110, v62 row_ror:2 row_mask:0xf bank_mask:0xf
	v_mov_b32_dpp v111, v63 row_ror:2 row_mask:0xf bank_mask:0xf
	v_mov_b32_dpp v222, v68 row_shr:1 row_mask:0xf bank_mask:0xf
	v_mov_b32_dpp v223, v69 row_shr:1 row_mask:0xf bank_mask:0xf
	v_mov_b32_dpp v224, v70 row_shr:1 row_mask:0xf bank_mask:0xf
	v_mov_b32_dpp v225, v71 row_shr:1 row_mask:0xf bank_mask:0xf
	v_mov_b32_dpp v230, v68 row_shr:2 row_mask:0xf bank_mask:0xf
	v_mov_b32_dpp v231, v69 row_shr:2 row_mask:0xf bank_mask:0xf
	v_mov_b32_dpp v232, v70 row_shr:2 row_mask:0xf bank_mask:0xf
	v_mov_b32_dpp v233, v71 row_shr:2 row_mask:0xf bank_mask:0xf
	v_mov_b32_dpp v226, v44 row_shr:1 row_mask:0xf bank_mask:0xf
	v_mov_b32_dpp v227, v45 row_shr:1 row_mask:0xf bank_mask:0xf
	v_mov_b32_dpp v228, v46 row_shr:1 row_mask:0xf bank_mask:0xf
	v_mov_b32_dpp v229, v47 row_shr:1 row_mask:0xf bank_mask:0xf
	v_mov_b32_dpp v108, v44 row_shr:2 row_mask:0xf bank_mask:0xf
	v_mov_b32_dpp v109, v45 row_shr:2 row_mask:0xf bank_mask:0xf
	v_mov_b32_dpp v110, v46 row_shr:2 row_mask:0xf bank_mask:0xf
	v_mov_b32_dpp v111, v47 row_shr:2 row_mask:0xf bank_mask:0xf
	v_mov_b32_dpp v132, v68 row_ror:1 row_mask:0xf bank_mask:0xf
	v_mov_b32_dpp v133, v69 row_ror:1 row_mask:0xf bank_mask:0xf
	v_mov_b32_dpp v134, v70 row_ror:1 row_mask:0xf bank_mask:0xf
	v_mov_b32_dpp v135, v71 row_ror:1 row_mask:0xf bank_mask:0xf
	v_mov_b32_dpp v156, v68 row_ror:2 row_mask:0xf bank_mask:0xf
	v_mov_b32_dpp v157, v69 row_ror:2 row_mask:0xf bank_mask:0xf
	v_mov_b32_dpp v158, v70 row_ror:2 row_mask:0xf bank_mask:0xf
	v_mov_b32_dpp v159, v71 row_ror:2 row_mask:0xf bank_mask:0xf
	v_mov_b32_dpp v136, v44 row_ror:1 row_mask:0xf bank_mask:0xf
	v_mov_b32_dpp v137, v45 row_ror:1 row_mask:0xf bank_mask:0xf
	v_mov_b32_dpp v138, v46 row_ror:1 row_mask:0xf bank_mask:0xf
	v_mov_b32_dpp v139, v47 row_ror:1 row_mask:0xf bank_mask:0xf
	v_mov_b32_dpp v160, v44 row_ror:2 row_mask:0xf bank_mask:0xf
	v_mov_b32_dpp v161, v45 row_ror:2 row_mask:0xf bank_mask:0xf
	v_mov_b32_dpp v162, v46 row_ror:2 row_mask:0xf bank_mask:0xf
	v_mov_b32_dpp v163, v47 row_ror:2 row_mask:0xf bank_mask:0xf
	v_pk_fma_f32 v[164:165], v[188:189], v[230:231], v[214:215]
	v_pk_fma_f32 v[166:167], v[190:191], v[232:233], v[216:217]
	v_pk_fma_f32 v[164:165], v[196:197], v[222:223], v[164:165]
	v_pk_fma_f32 v[166:167], v[198:199], v[224:225], v[166:167]
	v_pk_fma_f32 v[164:165], v[68:69], v[204:205], v[164:165]
	v_pk_fma_f32 v[166:167], v[70:71], v[206:207], v[166:167]
	v_pk_fma_f32 v[168:169], v[192:193], v[108:109], v[218:219]
	v_pk_fma_f32 v[170:171], v[194:195], v[110:111], v[220:221]
	v_pk_fma_f32 v[168:169], v[200:201], v[226:227], v[168:169]
	v_pk_fma_f32 v[170:171], v[202:203], v[228:229], v[170:171]
	v_pk_fma_f32 v[168:169], v[44:45], v[210:211], v[168:169]
	v_pk_fma_f32 v[170:171], v[46:47], v[212:213], v[170:171]
	v_mul_f32_e32 v222, 0xbfb8aa3b, v164
	v_mul_f32_e32 v223, 0xbfb8aa3b, v165
	v_mul_f32_e32 v224, 0xbfb8aa3b, v166
	v_mul_f32_e32 v225, 0xbfb8aa3b, v167
	v_exp_f32_e32 v222, v222
	v_exp_f32_e32 v223, v223
	v_exp_f32_e32 v224, v224
	v_exp_f32_e32 v225, v225
	v_add_f32_e32 v222, 1.0, v222
	v_add_f32_e32 v223, 1.0, v223
	v_add_f32_e32 v224, 1.0, v224
	v_add_f32_e32 v225, 1.0, v225
	v_rcp_f32_e32 v222, v222
	v_rcp_f32_e32 v223, v223
	v_rcp_f32_e32 v224, v224
	v_rcp_f32_e32 v225, v225
	v_mul_f32_e32 v164, v164, v222
	v_mul_f32_e32 v165, v165, v223
	v_mul_f32_e32 v166, v166, v224
	v_mul_f32_e32 v167, v167, v225
	v_mul_f32_e32 v164, v164, v168
	v_mul_f32_e32 v165, v165, v169
	v_mul_f32_e32 v166, v166, v170
	v_mul_f32_e32 v167, v167, v171
	v_cvt_pk_bf16_f32 v164, v164, v165
	v_cvt_pk_bf16_f32 v165, v166, v167
	v_add_u32_e32 v181, 0x18c000, v155
	global_store_dwordx2 v181, v[164:165], s[0:1]
	v_mov_b32_dpp v132, v52 row_shr:1 row_mask:0xf bank_mask:0xf
	v_mov_b32_dpp v133, v53 row_shr:1 row_mask:0xf bank_mask:0xf
	v_mov_b32_dpp v134, v54 row_shr:1 row_mask:0xf bank_mask:0xf
	v_mov_b32_dpp v135, v55 row_shr:1 row_mask:0xf bank_mask:0xf
; #define LAS __attribute__((address_space(3)))
; __device__ __forceinline__ unsigned cvt_pk_bf16(float lo, float hi) { unsigned r; asm volatile("v_cvt_pk_bf16_f32 %0, %1, %2" : "=v"(r) : "v"(lo), "v"(hi)); return r; }
; __device__ __forceinline__ float sigmoidf_(float x) { return __builtin_amdgcn_rcpf(1.0f + __expf(-x)); }
; __device__ __forceinline__ float dpp_ror1(float v) { return __int_as_float(__builtin_amdgcn_update_dpp(0, __float_as_int(v), 0x121, 0xf, 0xf, false)); }
; __device__ __forceinline__ float dpp_shr1(float old, float v) { return __int_as_float(__builtin_amdgcn_update_dpp(__float_as_int(old), __float_as_int(v), 0x111, 0xf, 0xf, false)); }
;     __device__ __forceinline__ void conv_rows(const f32x4 curg, const f32x4 curv, f32x4 (&q1)[2], f32x4 (&q2)[2], const LAS float* cp, bf16_t* dst, const bool upd) const {
;         f32x4 uc[2];
; #pragma unroll
;         for (int bj = 0; bj < 2; ++bj) {
;             const f32x4 c0 = *(const LAS f32x4*)(cp + bj * 32), c1 = *(const LAS f32x4*)(cp + bj * 32 + 64), c2 = *(const LAS f32x4*)(cp + bj * 32 + 128), bb = *(const LAS f32x4*)(cp + bj * 32 + 192);
;             const f32x4 cur = bj ? curv : curg;
; #pragma unroll
;             for (int e = 0; e < 4; ++e) {
;                 const float p1 = dpp_shr1(q1[bj][e], cur[e]), p2 = dpp_shr2(q2[bj][e], cur[e]);
;                 uc[bj][e] = bb[e] + c0[e] * p2 + c1[e] * p1 + c2[e] * cur[e];
;                 if (upd) { q1[bj][e] = dpp_ror1(cur[e]); q2[bj][e] = dpp_ror2(cur[e]); }
;             }
;         }
;         u32x2 w;
;         { const float a0 = uc[0][0] * sigmoidf_(uc[0][0]) * uc[1][0], a1 = uc[0][1] * sigmoidf_(uc[0][1]) * uc[1][1];
;           const float a2 = uc[0][2] * sigmoidf_(uc[0][2]) * uc[1][2], a3 = uc[0][3] * sigmoidf_(uc[0][3]) * uc[1][3];
;           w.x = cvt_pk_bf16(a0, a1); w.y = cvt_pk_bf16(a2, a3); }
;         *(u32x2*)dst = w;
;     __device__ __forceinline__ void operator()(f32x4 (&acc)[2][2][4][2], const Unit& u, int wr, int wc, int fr, int fq) const {
;     ...
;                     for (int e = 0; e < 4; ++e) { q1[bj][e] = dpp_ror1(acc[ai][bj][0][n][e]); q2[bj][e] = dpp_ror2(acc[ai][bj][0][n][e]); }
; #pragma unroll
;                 for (int m = 1; m < 4; ++m) conv_rows(acc[ai][0][m][n], acc[ai][1][m][n], q1, q2, cp, act + (size_t)(rowt + ai * HALF + m * 16) * FF + jcol, m < 3);
	v_mov_b32_dpp v156, v52 row_shr:2 row_mask:0xf bank_mask:0xf
	v_mov_b32_dpp v157, v53 row_shr:2 row_mask:0xf bank_mask:0xf
	v_mov_b32_dpp v158, v54 row_shr:2 row_mask:0xf bank_mask:0xf
	v_mov_b32_dpp v159, v55 row_shr:2 row_mask:0xf bank_mask:0xf
	v_mov_b32_dpp v136, v36 row_shr:1 row_mask:0xf bank_mask:0xf
	v_mov_b32_dpp v137, v37 row_shr:1 row_mask:0xf bank_mask:0xf
	v_mov_b32_dpp v138, v38 row_shr:1 row_mask:0xf bank_mask:0xf
	v_mov_b32_dpp v139, v39 row_shr:1 row_mask:0xf bank_mask:0xf
	v_mov_b32_dpp v160, v36 row_shr:2 row_mask:0xf bank_mask:0xf
	v_mov_b32_dpp v161, v37 row_shr:2 row_mask:0xf bank_mask:0xf
	v_mov_b32_dpp v162, v38 row_shr:2 row_mask:0xf bank_mask:0xf
	v_mov_b32_dpp v163, v39 row_shr:2 row_mask:0xf bank_mask:0xf
	v_mov_b32_dpp v222, v52 row_ror:1 row_mask:0xf bank_mask:0xf
	v_mov_b32_dpp v223, v53 row_ror:1 row_mask:0xf bank_mask:0xf
	v_mov_b32_dpp v224, v54 row_ror:1 row_mask:0xf bank_mask:0xf
	v_mov_b32_dpp v225, v55 row_ror:1 row_mask:0xf bank_mask:0xf
	v_mov_b32_dpp v230, v52 row_ror:2 row_mask:0xf bank_mask:0xf
	v_mov_b32_dpp v231, v53 row_ror:2 row_mask:0xf bank_mask:0xf
	v_mov_b32_dpp v232, v54 row_ror:2 row_mask:0xf bank_mask:0xf
	v_mov_b32_dpp v233, v55 row_ror:2 row_mask:0xf bank_mask:0xf
	v_mov_b32_dpp v226, v36 row_ror:1 row_mask:0xf bank_mask:0xf
	v_mov_b32_dpp v227, v37 row_ror:1 row_mask:0xf bank_mask:0xf
	v_mov_b32_dpp v228, v38 row_ror:1 row_mask:0xf bank_mask:0xf
	v_mov_b32_dpp v229, v39 row_ror:1 row_mask:0xf bank_mask:0xf
	v_mov_b32_dpp v108, v36 row_ror:2 row_mask:0xf bank_mask:0xf
	v_mov_b32_dpp v109, v37 row_ror:2 row_mask:0xf bank_mask:0xf
	v_mov_b32_dpp v110, v38 row_ror:2 row_mask:0xf bank_mask:0xf
	v_mov_b32_dpp v111, v39 row_ror:2 row_mask:0xf bank_mask:0xf
	v_pk_fma_f32 v[164:165], v[188:189], v[156:157], v[214:215]
	v_pk_fma_f32 v[166:167], v[190:191], v[158:159], v[216:217]
	v_pk_fma_f32 v[164:165], v[196:197], v[132:133], v[164:165]
	v_pk_fma_f32 v[166:167], v[198:199], v[134:135], v[166:167]
	v_pk_fma_f32 v[164:165], v[52:53], v[204:205], v[164:165]
	v_pk_fma_f32 v[166:167], v[54:55], v[206:207], v[166:167]
	v_pk_fma_f32 v[168:169], v[192:193], v[160:161], v[218:219]
	v_pk_fma_f32 v[170:171], v[194:195], v[162:163], v[220:221]
	v_pk_fma_f32 v[168:169], v[200:201], v[136:137], v[168:169]
	v_pk_fma_f32 v[170:171], v[202:203], v[138:139], v[170:171]
	v_pk_fma_f32 v[168:169], v[36:37], v[210:211], v[168:169]
	v_pk_fma_f32 v[170:171], v[38:39], v[212:213], v[170:171]
	v_mul_f32_e32 v132, 0xbfb8aa3b, v164
	v_mul_f32_e32 v133, 0xbfb8aa3b, v165
	v_mul_f32_e32 v134, 0xbfb8aa3b, v166
	v_mul_f32_e32 v135, 0xbfb8aa3b, v167
	v_exp_f32_e32 v132, v132
	v_exp_f32_e32 v133, v133
	v_exp_f32_e32 v134, v134
	v_exp_f32_e32 v135, v135
	v_add_f32_e32 v132, 1.0, v132
	v_add_f32_e32 v133, 1.0, v133
	v_add_f32_e32 v134, 1.0, v134
	v_add_f32_e32 v135, 1.0, v135
	v_rcp_f32_e32 v132, v132
	v_rcp_f32_e32 v133, v133
	v_rcp_f32_e32 v134, v134
	v_rcp_f32_e32 v135, v135
	v_mul_f32_e32 v164, v164, v132
	v_mul_f32_e32 v165, v165, v133
	v_mul_f32_e32 v166, v166, v134
	v_mul_f32_e32 v167, v167, v135
	v_mul_f32_e32 v164, v164, v168
	v_mul_f32_e32 v165, v165, v169
	v_mul_f32_e32 v166, v166, v170
	v_mul_f32_e32 v167, v167, v171
	v_cvt_pk_bf16_f32 v164, v164, v165
	v_cvt_pk_bf16_f32 v165, v166, v167
	v_add_u32_e32 v181, 0x1b8000, v155
	global_store_dwordx2 v181, v[164:165], s[0:1]
	v_mov_b32_dpp v222, v16 row_shr:1 row_mask:0xf bank_mask:0xf
	v_mov_b32_dpp v223, v17 row_shr:1 row_mask:0xf bank_mask:0xf
	v_mov_b32_dpp v224, v18 row_shr:1 row_mask:0xf bank_mask:0xf
	v_mov_b32_dpp v225, v19 row_shr:1 row_mask:0xf bank_mask:0xf
	v_mov_b32_dpp v230, v16 row_shr:2 row_mask:0xf bank_mask:0xf
	v_mov_b32_dpp v231, v17 row_shr:2 row_mask:0xf bank_mask:0xf
	v_mov_b32_dpp v232, v18 row_shr:2 row_mask:0xf bank_mask:0xf
	v_mov_b32_dpp v233, v19 row_shr:2 row_mask:0xf bank_mask:0xf
	v_mov_b32_dpp v226, v4 row_shr:1 row_mask:0xf bank_mask:0xf
	v_mov_b32_dpp v227, v5 row_shr:1 row_mask:0xf bank_mask:0xf
	v_mov_b32_dpp v228, v6 row_shr:1 row_mask:0xf bank_mask:0xf
	v_mov_b32_dpp v229, v7 row_shr:1 row_mask:0xf bank_mask:0xf
	v_mov_b32_dpp v108, v4 row_shr:2 row_mask:0xf bank_mask:0xf
	v_mov_b32_dpp v109, v5 row_shr:2 row_mask:0xf bank_mask:0xf
	v_mov_b32_dpp v110, v6 row_shr:2 row_mask:0xf bank_mask:0xf
	v_mov_b32_dpp v111, v7 row_shr:2 row_mask:0xf bank_mask:0xf
	v_pk_fma_f32 v[164:165], v[188:189], v[230:231], v[214:215]
	v_pk_fma_f32 v[166:167], v[190:191], v[232:233], v[216:217]
	v_pk_fma_f32 v[164:165], v[196:197], v[222:223], v[164:165]
	v_pk_fma_f32 v[166:167], v[198:199], v[224:225], v[166:167]
	v_pk_fma_f32 v[164:165], v[16:17], v[204:205], v[164:165]
	v_pk_fma_f32 v[166:167], v[18:19], v[206:207], v[166:167]
	v_pk_fma_f32 v[168:169], v[192:193], v[108:109], v[218:219]
	v_pk_fma_f32 v[170:171], v[194:195], v[110:111], v[220:221]
	v_pk_fma_f32 v[168:169], v[200:201], v[226:227], v[168:169]
	v_pk_fma_f32 v[170:171], v[202:203], v[228:229], v[170:171]
	v_pk_fma_f32 v[168:169], v[4:5], v[210:211], v[168:169]
	v_pk_fma_f32 v[170:171], v[6:7], v[212:213], v[170:171]
	v_mul_f32_e32 v222, 0xbfb8aa3b, v164
	v_mul_f32_e32 v223, 0xbfb8aa3b, v165
	v_mul_f32_e32 v224, 0xbfb8aa3b, v166
	v_mul_f32_e32 v225, 0xbfb8aa3b, v167
	v_exp_f32_e32 v222, v222
	v_exp_f32_e32 v223, v223
	v_exp_f32_e32 v224, v224
	v_exp_f32_e32 v225, v225
	v_add_f32_e32 v222, 1.0, v222
	v_add_f32_e32 v223, 1.0, v223
	v_add_f32_e32 v224, 1.0, v224
	v_add_f32_e32 v225, 1.0, v225
	v_rcp_f32_e32 v222, v222
	v_rcp_f32_e32 v223, v223
	v_rcp_f32_e32 v224, v224
	v_rcp_f32_e32 v225, v225
	v_mul_f32_e32 v164, v164, v222
	v_mul_f32_e32 v165, v165, v223
	v_mul_f32_e32 v166, v166, v224
; #define LAS __attribute__((address_space(3)))
; __device__ __forceinline__ unsigned cvt_pk_bf16(float lo, float hi) { unsigned r; asm volatile("v_cvt_pk_bf16_f32 %0, %1, %2" : "=v"(r) : "v"(lo), "v"(hi)); return r; }
; __device__ __forceinline__ float sigmoidf_(float x) { return __builtin_amdgcn_rcpf(1.0f + __expf(-x)); }
;     __device__ __forceinline__ void conv_rows(const f32x4 curg, const f32x4 curv, f32x4 (&q1)[2], f32x4 (&q2)[2], const LAS float* cp, bf16_t* dst, const bool upd) const {
;         f32x4 uc[2];
; #pragma unroll
;         for (int bj = 0; bj < 2; ++bj) {
;             const f32x4 c0 = *(const LAS f32x4*)(cp + bj * 32), c1 = *(const LAS f32x4*)(cp + bj * 32 + 64), c2 = *(const LAS f32x4*)(cp + bj * 32 + 128), bb = *(const LAS f32x4*)(cp + bj * 32 + 192);
;             const f32x4 cur = bj ? curv : curg;
; #pragma unroll
;             for (int e = 0; e < 4; ++e) {
;                 const float p1 = dpp_shr1(q1[bj][e], cur[e]), p2 = dpp_shr2(q2[bj][e], cur[e]);
;                 uc[bj][e] = bb[e] + c0[e] * p2 + c1[e] * p1 + c2[e] * cur[e];
;                 if (upd) { q1[bj][e] = dpp_ror1(cur[e]); q2[bj][e] = dpp_ror2(cur[e]); }
;             }
;         }
;         u32x2 w;
;         { const float a0 = uc[0][0] * sigmoidf_(uc[0][0]) * uc[1][0], a1 = uc[0][1] * sigmoidf_(uc[0][1]) * uc[1][1];
;           const float a2 = uc[0][2] * sigmoidf_(uc[0][2]) * uc[1][2], a3 = uc[0][3] * sigmoidf_(uc[0][3]) * uc[1][3];
;           w.x = cvt_pk_bf16(a0, a1); w.y = cvt_pk_bf16(a2, a3); }
;         *(u32x2*)dst = w;
;     __device__ __forceinline__ void operator()(f32x4 (&acc)[2][2][4][2], const Unit& u, int wr, int wc, int fr, int fq) const {
;     ...
;         for (int n = 0; n < 2; ++n) {
;             const int jcol = u.pn * HALF + cl0 + n * 16; const LAS float* cp = myc + 16 * n + 4 * fq;
; #pragma unroll
;             for (int ai = 0; ai < 2; ++ai) {
;                 f32x4 q1[2], q2[2];
; #pragma unroll
;                 for (int bj = 0; bj < 2; ++bj)
; #pragma unroll
;                     for (int e = 0; e < 4; ++e) { q1[bj][e] = dpp_ror1(acc[ai][bj][0][n][e]); q2[bj][e] = dpp_ror2(acc[ai][bj][0][n][e]); }
; #pragma unroll
;                 for (int m = 1; m < 4; ++m) conv_rows(acc[ai][0][m][n], acc[ai][1][m][n], q1, q2, cp, act + (size_t)(rowt + ai * HALF + m * 16) * FF + jcol, m < 3);
	v_mul_f32_e32 v167, v167, v225
	v_mul_f32_e32 v164, v164, v168
	v_mul_f32_e32 v165, v165, v169
	v_mul_f32_e32 v166, v166, v170
	v_mul_f32_e32 v167, v167, v171
	v_cvt_pk_bf16_f32 v164, v164, v165
	v_cvt_pk_bf16_f32 v165, v166, v167
	v_add_u32_e32 v181, 0x1e4000, v155
	global_store_dwordx2 v181, v[164:165], s[0:1]
	ds_read_b128 v[188:191], v153 offset:64
	ds_read_b128 v[192:195], v153 offset:192
	ds_read_b128 v[196:199], v153 offset:320
	ds_read_b128 v[200:203], v153 offset:448
	ds_read_b128 v[204:207], v153 offset:576
	ds_read_b128 v[210:213], v153 offset:704
	ds_read_b128 v[214:217], v153 offset:832
	ds_read_b128 v[218:221], v153 offset:960
	v_mov_b32_dpp v222, v124 row_ror:1 row_mask:0xf bank_mask:0xf
	v_mov_b32_dpp v223, v125 row_ror:1 row_mask:0xf bank_mask:0xf
	v_mov_b32_dpp v224, v126 row_ror:1 row_mask:0xf bank_mask:0xf
	v_mov_b32_dpp v225, v127 row_ror:1 row_mask:0xf bank_mask:0xf
	v_mov_b32_dpp v230, v124 row_ror:2 row_mask:0xf bank_mask:0xf
	v_mov_b32_dpp v231, v125 row_ror:2 row_mask:0xf bank_mask:0xf
	v_mov_b32_dpp v232, v126 row_ror:2 row_mask:0xf bank_mask:0xf
	v_mov_b32_dpp v233, v127 row_ror:2 row_mask:0xf bank_mask:0xf
	v_mov_b32_dpp v226, v120 row_ror:1 row_mask:0xf bank_mask:0xf
	v_mov_b32_dpp v227, v121 row_ror:1 row_mask:0xf bank_mask:0xf
	v_mov_b32_dpp v228, v122 row_ror:1 row_mask:0xf bank_mask:0xf
	v_mov_b32_dpp v229, v123 row_ror:1 row_mask:0xf bank_mask:0xf
	v_mov_b32_dpp v108, v120 row_ror:2 row_mask:0xf bank_mask:0xf
	v_mov_b32_dpp v109, v121 row_ror:2 row_mask:0xf bank_mask:0xf
	v_mov_b32_dpp v110, v122 row_ror:2 row_mask:0xf bank_mask:0xf
	v_mov_b32_dpp v111, v123 row_ror:2 row_mask:0xf bank_mask:0xf
	s_waitcnt lgkmcnt(0)
	v_mov_b32_dpp v222, v112 row_shr:1 row_mask:0xf bank_mask:0xf
	v_mov_b32_dpp v223, v113 row_shr:1 row_mask:0xf bank_mask:0xf
	v_mov_b32_dpp v224, v114 row_shr:1 row_mask:0xf bank_mask:0xf
	v_mov_b32_dpp v225, v115 row_shr:1 row_mask:0xf bank_mask:0xf
	v_mov_b32_dpp v230, v112 row_shr:2 row_mask:0xf bank_mask:0xf
	v_mov_b32_dpp v231, v113 row_shr:2 row_mask:0xf bank_mask:0xf
	v_mov_b32_dpp v232, v114 row_shr:2 row_mask:0xf bank_mask:0xf
	v_mov_b32_dpp v233, v115 row_shr:2 row_mask:0xf bank_mask:0xf
	v_mov_b32_dpp v226, v92 row_shr:1 row_mask:0xf bank_mask:0xf
	v_mov_b32_dpp v227, v93 row_shr:1 row_mask:0xf bank_mask:0xf
	v_mov_b32_dpp v228, v94 row_shr:1 row_mask:0xf bank_mask:0xf
	v_mov_b32_dpp v229, v95 row_shr:1 row_mask:0xf bank_mask:0xf
	v_mov_b32_dpp v108, v92 row_shr:2 row_mask:0xf bank_mask:0xf
	v_mov_b32_dpp v109, v93 row_shr:2 row_mask:0xf bank_mask:0xf
	v_mov_b32_dpp v110, v94 row_shr:2 row_mask:0xf bank_mask:0xf
	v_mov_b32_dpp v111, v95 row_shr:2 row_mask:0xf bank_mask:0xf
	v_mov_b32_dpp v132, v112 row_ror:1 row_mask:0xf bank_mask:0xf
	v_mov_b32_dpp v133, v113 row_ror:1 row_mask:0xf bank_mask:0xf
	v_mov_b32_dpp v134, v114 row_ror:1 row_mask:0xf bank_mask:0xf
	v_mov_b32_dpp v135, v115 row_ror:1 row_mask:0xf bank_mask:0xf
	v_mov_b32_dpp v156, v112 row_ror:2 row_mask:0xf bank_mask:0xf
	v_mov_b32_dpp v157, v113 row_ror:2 row_mask:0xf bank_mask:0xf
	v_mov_b32_dpp v158, v114 row_ror:2 row_mask:0xf bank_mask:0xf
	v_mov_b32_dpp v159, v115 row_ror:2 row_mask:0xf bank_mask:0xf
	v_mov_b32_dpp v136, v92 row_ror:1 row_mask:0xf bank_mask:0xf
	v_mov_b32_dpp v137, v93 row_ror:1 row_mask:0xf bank_mask:0xf
	v_mov_b32_dpp v138, v94 row_ror:1 row_mask:0xf bank_mask:0xf
	v_mov_b32_dpp v139, v95 row_ror:1 row_mask:0xf bank_mask:0xf
	v_mov_b32_dpp v160, v92 row_ror:2 row_mask:0xf bank_mask:0xf
	v_mov_b32_dpp v161, v93 row_ror:2 row_mask:0xf bank_mask:0xf
	v_mov_b32_dpp v162, v94 row_ror:2 row_mask:0xf bank_mask:0xf
	v_mov_b32_dpp v163, v95 row_ror:2 row_mask:0xf bank_mask:0xf
	v_pk_fma_f32 v[164:165], v[188:189], v[230:231], v[214:215]
	v_pk_fma_f32 v[166:167], v[190:191], v[232:233], v[216:217]
	v_pk_fma_f32 v[164:165], v[196:197], v[222:223], v[164:165]
	v_pk_fma_f32 v[166:167], v[198:199], v[224:225], v[166:167]
	v_pk_fma_f32 v[164:165], v[112:113], v[204:205], v[164:165]
	v_pk_fma_f32 v[166:167], v[114:115], v[206:207], v[166:167]
	v_pk_fma_f32 v[168:169], v[192:193], v[108:109], v[218:219]
	v_pk_fma_f32 v[170:171], v[194:195], v[110:111], v[220:221]
	v_pk_fma_f32 v[168:169], v[200:201], v[226:227], v[168:169]
	v_pk_fma_f32 v[170:171], v[202:203], v[228:229], v[170:171]
	v_pk_fma_f32 v[168:169], v[92:93], v[210:211], v[168:169]
	v_pk_fma_f32 v[170:171], v[94:95], v[212:213], v[170:171]
	v_mul_f32_e32 v222, 0xbfb8aa3b, v164
	v_mul_f32_e32 v223, 0xbfb8aa3b, v165
	v_mul_f32_e32 v224, 0xbfb8aa3b, v166
	v_mul_f32_e32 v225, 0xbfb8aa3b, v167
	v_exp_f32_e32 v222, v222
	v_exp_f32_e32 v223, v223
	v_exp_f32_e32 v224, v224
	v_exp_f32_e32 v225, v225
	v_add_f32_e32 v222, 1.0, v222
	v_add_f32_e32 v223, 1.0, v223
	v_add_f32_e32 v224, 1.0, v224
	v_add_f32_e32 v225, 1.0, v225
	v_rcp_f32_e32 v222, v222
	v_rcp_f32_e32 v223, v223
	v_rcp_f32_e32 v224, v224
	v_rcp_f32_e32 v225, v225
	v_mul_f32_e32 v164, v164, v222
	v_mul_f32_e32 v165, v165, v223
	v_mul_f32_e32 v166, v166, v224
	v_mul_f32_e32 v167, v167, v225
	v_mul_f32_e32 v164, v164, v168
	v_mul_f32_e32 v165, v165, v169
	v_mul_f32_e32 v166, v166, v170
	v_mul_f32_e32 v167, v167, v171
	v_cvt_pk_bf16_f32 v164, v164, v165
	v_cvt_pk_bf16_f32 v165, v166, v167
	v_add_u32_e32 v181, 0x2c000, v155
	global_store_dwordx2 v181, v[164:165], s[0:1] offset:32
	v_mov_b32_dpp v132, v96 row_shr:1 row_mask:0xf bank_mask:0xf
	v_mov_b32_dpp v133, v97 row_shr:1 row_mask:0xf bank_mask:0xf
	v_mov_b32_dpp v134, v98 row_shr:1 row_mask:0xf bank_mask:0xf
	v_mov_b32_dpp v135, v99 row_shr:1 row_mask:0xf bank_mask:0xf
	v_mov_b32_dpp v156, v96 row_shr:2 row_mask:0xf bank_mask:0xf
; #define LAS __attribute__((address_space(3)))
; __device__ __forceinline__ unsigned cvt_pk_bf16(float lo, float hi) { unsigned r; asm volatile("v_cvt_pk_bf16_f32 %0, %1, %2" : "=v"(r) : "v"(lo), "v"(hi)); return r; }
; __device__ __forceinline__ float sigmoidf_(float x) { return __builtin_amdgcn_rcpf(1.0f + __expf(-x)); }
; __device__ __forceinline__ float dpp_ror1(float v) { return __int_as_float(__builtin_amdgcn_update_dpp(0, __float_as_int(v), 0x121, 0xf, 0xf, false)); }
; __device__ __forceinline__ float dpp_shr1(float old, float v) { return __int_as_float(__builtin_amdgcn_update_dpp(__float_as_int(old), __float_as_int(v), 0x111, 0xf, 0xf, false)); }
;     __device__ __forceinline__ void conv_rows(const f32x4 curg, const f32x4 curv, f32x4 (&q1)[2], f32x4 (&q2)[2], const LAS float* cp, bf16_t* dst, const bool upd) const {
;         f32x4 uc[2];
; #pragma unroll
;         for (int bj = 0; bj < 2; ++bj) {
;             const f32x4 c0 = *(const LAS f32x4*)(cp + bj * 32), c1 = *(const LAS f32x4*)(cp + bj * 32 + 64), c2 = *(const LAS f32x4*)(cp + bj * 32 + 128), bb = *(const LAS f32x4*)(cp + bj * 32 + 192);
;             const f32x4 cur = bj ? curv : curg;
; #pragma unroll
;             for (int e = 0; e < 4; ++e) {
;                 const float p1 = dpp_shr1(q1[bj][e], cur[e]), p2 = dpp_shr2(q2[bj][e], cur[e]);
;                 uc[bj][e] = bb[e] + c0[e] * p2 + c1[e] * p1 + c2[e] * cur[e];
;                 if (upd) { q1[bj][e] = dpp_ror1(cur[e]); q2[bj][e] = dpp_ror2(cur[e]); }
;             }
;         }
;         u32x2 w;
;         { const float a0 = uc[0][0] * sigmoidf_(uc[0][0]) * uc[1][0], a1 = uc[0][1] * sigmoidf_(uc[0][1]) * uc[1][1];
;           const float a2 = uc[0][2] * sigmoidf_(uc[0][2]) * uc[1][2], a3 = uc[0][3] * sigmoidf_(uc[0][3]) * uc[1][3];
;           w.x = cvt_pk_bf16(a0, a1); w.y = cvt_pk_bf16(a2, a3); }
;         *(u32x2*)dst = w;
;     __device__ __forceinline__ void operator()(f32x4 (&acc)[2][2][4][2], const Unit& u, int wr, int wc, int fr, int fq) const {
;     ...
;                     for (int e = 0; e < 4; ++e) { q1[bj][e] = dpp_ror1(acc[ai][bj][0][n][e]); q2[bj][e] = dpp_ror2(acc[ai][bj][0][n][e]); }
; #pragma unroll
;                 for (int m = 1; m < 4; ++m) conv_rows(acc[ai][0][m][n], acc[ai][1][m][n], q1, q2, cp, act + (size_t)(rowt + ai * HALF + m * 16) * FF + jcol, m < 3);
	v_mov_b32_dpp v157, v97 row_shr:2 row_mask:0xf bank_mask:0xf
	v_mov_b32_dpp v158, v98 row_shr:2 row_mask:0xf bank_mask:0xf
	v_mov_b32_dpp v159, v99 row_shr:2 row_mask:0xf bank_mask:0xf
	v_mov_b32_dpp v136, v80 row_shr:1 row_mask:0xf bank_mask:0xf
	v_mov_b32_dpp v137, v81 row_shr:1 row_mask:0xf bank_mask:0xf
	v_mov_b32_dpp v138, v82 row_shr:1 row_mask:0xf bank_mask:0xf
	v_mov_b32_dpp v139, v83 row_shr:1 row_mask:0xf bank_mask:0xf
	v_mov_b32_dpp v160, v80 row_shr:2 row_mask:0xf bank_mask:0xf
	v_mov_b32_dpp v161, v81 row_shr:2 row_mask:0xf bank_mask:0xf
	v_mov_b32_dpp v162, v82 row_shr:2 row_mask:0xf bank_mask:0xf
	v_mov_b32_dpp v163, v83 row_shr:2 row_mask:0xf bank_mask:0xf
	v_mov_b32_dpp v222, v96 row_ror:1 row_mask:0xf bank_mask:0xf
	v_mov_b32_dpp v223, v97 row_ror:1 row_mask:0xf bank_mask:0xf
	v_mov_b32_dpp v224, v98 row_ror:1 row_mask:0xf bank_mask:0xf
	v_mov_b32_dpp v225, v99 row_ror:1 row_mask:0xf bank_mask:0xf
	v_mov_b32_dpp v230, v96 row_ror:2 row_mask:0xf bank_mask:0xf
	v_mov_b32_dpp v231, v97 row_ror:2 row_mask:0xf bank_mask:0xf
	v_mov_b32_dpp v232, v98 row_ror:2 row_mask:0xf bank_mask:0xf
	v_mov_b32_dpp v233, v99 row_ror:2 row_mask:0xf bank_mask:0xf
	v_mov_b32_dpp v226, v80 row_ror:1 row_mask:0xf bank_mask:0xf
	v_mov_b32_dpp v227, v81 row_ror:1 row_mask:0xf bank_mask:0xf
	v_mov_b32_dpp v228, v82 row_ror:1 row_mask:0xf bank_mask:0xf
	v_mov_b32_dpp v229, v83 row_ror:1 row_mask:0xf bank_mask:0xf
	v_mov_b32_dpp v108, v80 row_ror:2 row_mask:0xf bank_mask:0xf
	v_mov_b32_dpp v109, v81 row_ror:2 row_mask:0xf bank_mask:0xf
	v_mov_b32_dpp v110, v82 row_ror:2 row_mask:0xf bank_mask:0xf
	v_mov_b32_dpp v111, v83 row_ror:2 row_mask:0xf bank_mask:0xf
	v_pk_fma_f32 v[164:165], v[188:189], v[156:157], v[214:215]
	v_pk_fma_f32 v[166:167], v[190:191], v[158:159], v[216:217]
	v_pk_fma_f32 v[164:165], v[196:197], v[132:133], v[164:165]
	v_pk_fma_f32 v[166:167], v[198:199], v[134:135], v[166:167]
	v_pk_fma_f32 v[164:165], v[96:97], v[204:205], v[164:165]
	v_pk_fma_f32 v[166:167], v[98:99], v[206:207], v[166:167]
	v_pk_fma_f32 v[168:169], v[192:193], v[160:161], v[218:219]
	v_pk_fma_f32 v[170:171], v[194:195], v[162:163], v[220:221]
	v_pk_fma_f32 v[168:169], v[200:201], v[136:137], v[168:169]
	v_pk_fma_f32 v[170:171], v[202:203], v[138:139], v[170:171]
	v_pk_fma_f32 v[168:169], v[80:81], v[210:211], v[168:169]
	v_pk_fma_f32 v[170:171], v[82:83], v[212:213], v[170:171]
	v_mul_f32_e32 v132, 0xbfb8aa3b, v164
	v_mul_f32_e32 v133, 0xbfb8aa3b, v165
	v_mul_f32_e32 v134, 0xbfb8aa3b, v166
	v_mul_f32_e32 v135, 0xbfb8aa3b, v167
	v_exp_f32_e32 v132, v132
	v_exp_f32_e32 v133, v133
	v_exp_f32_e32 v134, v134
	v_exp_f32_e32 v135, v135
	v_add_f32_e32 v132, 1.0, v132
	v_add_f32_e32 v133, 1.0, v133
	v_add_f32_e32 v134, 1.0, v134
	v_add_f32_e32 v135, 1.0, v135
	v_rcp_f32_e32 v132, v132
	v_rcp_f32_e32 v133, v133
	v_rcp_f32_e32 v134, v134
	v_rcp_f32_e32 v135, v135
	v_mul_f32_e32 v164, v164, v132
	v_mul_f32_e32 v165, v165, v133
	v_mul_f32_e32 v166, v166, v134
	v_mul_f32_e32 v167, v167, v135
	v_mul_f32_e32 v164, v164, v168
	v_mul_f32_e32 v165, v165, v169
	v_mul_f32_e32 v166, v166, v170
	v_mul_f32_e32 v167, v167, v171
	v_cvt_pk_bf16_f32 v164, v164, v165
	v_cvt_pk_bf16_f32 v165, v166, v167
	v_add_u32_e32 v181, 0x58000, v155
	global_store_dwordx2 v181, v[164:165], s[0:1] offset:32
	v_mov_b32_dpp v222, v24 row_shr:1 row_mask:0xf bank_mask:0xf
	v_mov_b32_dpp v223, v25 row_shr:1 row_mask:0xf bank_mask:0xf
	v_mov_b32_dpp v224, v26 row_shr:1 row_mask:0xf bank_mask:0xf
	v_mov_b32_dpp v225, v27 row_shr:1 row_mask:0xf bank_mask:0xf
	v_mov_b32_dpp v230, v24 row_shr:2 row_mask:0xf bank_mask:0xf
	v_mov_b32_dpp v231, v25 row_shr:2 row_mask:0xf bank_mask:0xf
	v_mov_b32_dpp v232, v26 row_shr:2 row_mask:0xf bank_mask:0xf
	v_mov_b32_dpp v233, v27 row_shr:2 row_mask:0xf bank_mask:0xf
	v_mov_b32_dpp v226, v20 row_shr:1 row_mask:0xf bank_mask:0xf
	v_mov_b32_dpp v227, v21 row_shr:1 row_mask:0xf bank_mask:0xf
	v_mov_b32_dpp v228, v22 row_shr:1 row_mask:0xf bank_mask:0xf
	v_mov_b32_dpp v229, v23 row_shr:1 row_mask:0xf bank_mask:0xf
	v_mov_b32_dpp v108, v20 row_shr:2 row_mask:0xf bank_mask:0xf
	v_mov_b32_dpp v109, v21 row_shr:2 row_mask:0xf bank_mask:0xf
	v_mov_b32_dpp v110, v22 row_shr:2 row_mask:0xf bank_mask:0xf
	v_mov_b32_dpp v111, v23 row_shr:2 row_mask:0xf bank_mask:0xf
	v_pk_fma_f32 v[164:165], v[188:189], v[230:231], v[214:215]
	v_pk_fma_f32 v[166:167], v[190:191], v[232:233], v[216:217]
	v_pk_fma_f32 v[164:165], v[196:197], v[222:223], v[164:165]
	v_pk_fma_f32 v[166:167], v[198:199], v[224:225], v[166:167]
	v_pk_fma_f32 v[164:165], v[24:25], v[204:205], v[164:165]
	v_pk_fma_f32 v[166:167], v[26:27], v[206:207], v[166:167]
	v_pk_fma_f32 v[168:169], v[192:193], v[108:109], v[218:219]
	v_pk_fma_f32 v[170:171], v[194:195], v[110:111], v[220:221]
	v_pk_fma_f32 v[168:169], v[200:201], v[226:227], v[168:169]
	v_pk_fma_f32 v[170:171], v[202:203], v[228:229], v[170:171]
	v_pk_fma_f32 v[168:169], v[20:21], v[210:211], v[168:169]
	v_pk_fma_f32 v[170:171], v[22:23], v[212:213], v[170:171]
	v_mul_f32_e32 v222, 0xbfb8aa3b, v164
	v_mul_f32_e32 v223, 0xbfb8aa3b, v165
	v_mul_f32_e32 v224, 0xbfb8aa3b, v166
	v_mul_f32_e32 v225, 0xbfb8aa3b, v167
	v_exp_f32_e32 v222, v222
	v_exp_f32_e32 v223, v223
	v_exp_f32_e32 v224, v224
	v_exp_f32_e32 v225, v225
	v_add_f32_e32 v222, 1.0, v222
	v_add_f32_e32 v223, 1.0, v223
	v_add_f32_e32 v224, 1.0, v224
	v_add_f32_e32 v225, 1.0, v225
	v_rcp_f32_e32 v222, v222
	v_rcp_f32_e32 v223, v223
	v_rcp_f32_e32 v224, v224
	v_rcp_f32_e32 v225, v225
	v_mul_f32_e32 v164, v164, v222
	v_mul_f32_e32 v165, v165, v223
	v_mul_f32_e32 v166, v166, v224
	v_mul_f32_e32 v167, v167, v225
; #define LAS __attribute__((address_space(3)))
; __device__ __forceinline__ unsigned cvt_pk_bf16(float lo, float hi) { unsigned r; asm volatile("v_cvt_pk_bf16_f32 %0, %1, %2" : "=v"(r) : "v"(lo), "v"(hi)); return r; }
; __device__ __forceinline__ float sigmoidf_(float x) { return __builtin_amdgcn_rcpf(1.0f + __expf(-x)); }
; __device__ __forceinline__ float dpp_ror1(float v) { return __int_as_float(__builtin_amdgcn_update_dpp(0, __float_as_int(v), 0x121, 0xf, 0xf, false)); }
;     __device__ __forceinline__ void conv_rows(const f32x4 curg, const f32x4 curv, f32x4 (&q1)[2], f32x4 (&q2)[2], const LAS float* cp, bf16_t* dst, const bool upd) const {
;         f32x4 uc[2];
; #pragma unroll
;         for (int bj = 0; bj < 2; ++bj) {
;             const f32x4 c0 = *(const LAS f32x4*)(cp + bj * 32), c1 = *(const LAS f32x4*)(cp + bj * 32 + 64), c2 = *(const LAS f32x4*)(cp + bj * 32 + 128), bb = *(const LAS f32x4*)(cp + bj * 32 + 192);
;             const f32x4 cur = bj ? curv : curg;
; #pragma unroll
;             for (int e = 0; e < 4; ++e) {
;                 const float p1 = dpp_shr1(q1[bj][e], cur[e]), p2 = dpp_shr2(q2[bj][e], cur[e]);
;                 uc[bj][e] = bb[e] + c0[e] * p2 + c1[e] * p1 + c2[e] * cur[e];
;                 if (upd) { q1[bj][e] = dpp_ror1(cur[e]); q2[bj][e] = dpp_ror2(cur[e]); }
;             }
;         }
;         u32x2 w;
;         { const float a0 = uc[0][0] * sigmoidf_(uc[0][0]) * uc[1][0], a1 = uc[0][1] * sigmoidf_(uc[0][1]) * uc[1][1];
;           const float a2 = uc[0][2] * sigmoidf_(uc[0][2]) * uc[1][2], a3 = uc[0][3] * sigmoidf_(uc[0][3]) * uc[1][3];
;           w.x = cvt_pk_bf16(a0, a1); w.y = cvt_pk_bf16(a2, a3); }
;         *(u32x2*)dst = w;
;     __device__ __forceinline__ void operator()(f32x4 (&acc)[2][2][4][2], const Unit& u, int wr, int wc, int fr, int fq) const {
;     ...
;             for (int ai = 0; ai < 2; ++ai) {
;                 f32x4 q1[2], q2[2];
; #pragma unroll
;                 for (int bj = 0; bj < 2; ++bj)
; #pragma unroll
;                     for (int e = 0; e < 4; ++e) { q1[bj][e] = dpp_ror1(acc[ai][bj][0][n][e]); q2[bj][e] = dpp_ror2(acc[ai][bj][0][n][e]); }
; #pragma unroll
;                 for (int m = 1; m < 4; ++m) conv_rows(acc[ai][0][m][n], acc[ai][1][m][n], q1, q2, cp, act + (size_t)(rowt + ai * HALF + m * 16) * FF + jcol, m < 3);
	v_mul_f32_e32 v164, v164, v168
	v_mul_f32_e32 v165, v165, v169
	v_mul_f32_e32 v166, v166, v170
	v_mul_f32_e32 v167, v167, v171
	v_cvt_pk_bf16_f32 v164, v164, v165
	v_cvt_pk_bf16_f32 v165, v166, v167
	v_add_u32_e32 v181, 0x84000, v155
	global_store_dwordx2 v181, v[164:165], s[0:1] offset:32
	v_mov_b32_dpp v222, v72 row_ror:1 row_mask:0xf bank_mask:0xf
	v_mov_b32_dpp v223, v73 row_ror:1 row_mask:0xf bank_mask:0xf
	v_mov_b32_dpp v224, v74 row_ror:1 row_mask:0xf bank_mask:0xf
	v_mov_b32_dpp v225, v75 row_ror:1 row_mask:0xf bank_mask:0xf
	v_mov_b32_dpp v230, v72 row_ror:2 row_mask:0xf bank_mask:0xf
	v_mov_b32_dpp v231, v73 row_ror:2 row_mask:0xf bank_mask:0xf
	v_mov_b32_dpp v232, v74 row_ror:2 row_mask:0xf bank_mask:0xf
	v_mov_b32_dpp v233, v75 row_ror:2 row_mask:0xf bank_mask:0xf
	v_mov_b32_dpp v226, v56 row_ror:1 row_mask:0xf bank_mask:0xf
	v_mov_b32_dpp v227, v57 row_ror:1 row_mask:0xf bank_mask:0xf
	v_mov_b32_dpp v228, v58 row_ror:1 row_mask:0xf bank_mask:0xf
	v_mov_b32_dpp v229, v59 row_ror:1 row_mask:0xf bank_mask:0xf
	v_mov_b32_dpp v108, v56 row_ror:2 row_mask:0xf bank_mask:0xf
	v_mov_b32_dpp v109, v57 row_ror:2 row_mask:0xf bank_mask:0xf
	v_mov_b32_dpp v110, v58 row_ror:2 row_mask:0xf bank_mask:0xf
	v_mov_b32_dpp v111, v59 row_ror:2 row_mask:0xf bank_mask:0xf
	v_mov_b32_dpp v222, v64 row_shr:1 row_mask:0xf bank_mask:0xf
	v_mov_b32_dpp v223, v65 row_shr:1 row_mask:0xf bank_mask:0xf
	v_mov_b32_dpp v224, v66 row_shr:1 row_mask:0xf bank_mask:0xf
	v_mov_b32_dpp v225, v67 row_shr:1 row_mask:0xf bank_mask:0xf
	v_mov_b32_dpp v230, v64 row_shr:2 row_mask:0xf bank_mask:0xf
	v_mov_b32_dpp v231, v65 row_shr:2 row_mask:0xf bank_mask:0xf
	v_mov_b32_dpp v232, v66 row_shr:2 row_mask:0xf bank_mask:0xf
	v_mov_b32_dpp v233, v67 row_shr:2 row_mask:0xf bank_mask:0xf
	v_mov_b32_dpp v226, v40 row_shr:1 row_mask:0xf bank_mask:0xf
	v_mov_b32_dpp v227, v41 row_shr:1 row_mask:0xf bank_mask:0xf
	v_mov_b32_dpp v228, v42 row_shr:1 row_mask:0xf bank_mask:0xf
	v_mov_b32_dpp v229, v43 row_shr:1 row_mask:0xf bank_mask:0xf
	v_mov_b32_dpp v108, v40 row_shr:2 row_mask:0xf bank_mask:0xf
	v_mov_b32_dpp v109, v41 row_shr:2 row_mask:0xf bank_mask:0xf
	v_mov_b32_dpp v110, v42 row_shr:2 row_mask:0xf bank_mask:0xf
	v_mov_b32_dpp v111, v43 row_shr:2 row_mask:0xf bank_mask:0xf
	v_mov_b32_dpp v132, v64 row_ror:1 row_mask:0xf bank_mask:0xf
	v_mov_b32_dpp v133, v65 row_ror:1 row_mask:0xf bank_mask:0xf
	v_mov_b32_dpp v134, v66 row_ror:1 row_mask:0xf bank_mask:0xf
	v_mov_b32_dpp v135, v67 row_ror:1 row_mask:0xf bank_mask:0xf
	v_mov_b32_dpp v156, v64 row_ror:2 row_mask:0xf bank_mask:0xf
	v_mov_b32_dpp v157, v65 row_ror:2 row_mask:0xf bank_mask:0xf
	v_mov_b32_dpp v158, v66 row_ror:2 row_mask:0xf bank_mask:0xf
	v_mov_b32_dpp v159, v67 row_ror:2 row_mask:0xf bank_mask:0xf
	v_mov_b32_dpp v136, v40 row_ror:1 row_mask:0xf bank_mask:0xf
	v_mov_b32_dpp v137, v41 row_ror:1 row_mask:0xf bank_mask:0xf
	v_mov_b32_dpp v138, v42 row_ror:1 row_mask:0xf bank_mask:0xf
	v_mov_b32_dpp v139, v43 row_ror:1 row_mask:0xf bank_mask:0xf
	v_mov_b32_dpp v160, v40 row_ror:2 row_mask:0xf bank_mask:0xf
	v_mov_b32_dpp v161, v41 row_ror:2 row_mask:0xf bank_mask:0xf
	v_mov_b32_dpp v162, v42 row_ror:2 row_mask:0xf bank_mask:0xf
	v_mov_b32_dpp v163, v43 row_ror:2 row_mask:0xf bank_mask:0xf
	v_pk_fma_f32 v[164:165], v[188:189], v[230:231], v[214:215]
	v_pk_fma_f32 v[166:167], v[190:191], v[232:233], v[216:217]
	v_pk_fma_f32 v[164:165], v[196:197], v[222:223], v[164:165]
	v_pk_fma_f32 v[166:167], v[198:199], v[224:225], v[166:167]
	v_pk_fma_f32 v[164:165], v[64:65], v[204:205], v[164:165]
	v_pk_fma_f32 v[166:167], v[66:67], v[206:207], v[166:167]
	v_pk_fma_f32 v[168:169], v[192:193], v[108:109], v[218:219]
	v_pk_fma_f32 v[170:171], v[194:195], v[110:111], v[220:221]
	v_pk_fma_f32 v[168:169], v[200:201], v[226:227], v[168:169]
	v_pk_fma_f32 v[170:171], v[202:203], v[228:229], v[170:171]
	v_pk_fma_f32 v[168:169], v[40:41], v[210:211], v[168:169]
	v_pk_fma_f32 v[170:171], v[42:43], v[212:213], v[170:171]
	v_mul_f32_e32 v222, 0xbfb8aa3b, v164
	v_mul_f32_e32 v223, 0xbfb8aa3b, v165
	v_mul_f32_e32 v224, 0xbfb8aa3b, v166
	v_mul_f32_e32 v225, 0xbfb8aa3b, v167
	v_exp_f32_e32 v222, v222
	v_exp_f32_e32 v223, v223
	v_exp_f32_e32 v224, v224
	v_exp_f32_e32 v225, v225
	v_add_f32_e32 v222, 1.0, v222
	v_add_f32_e32 v223, 1.0, v223
	v_add_f32_e32 v224, 1.0, v224
	v_add_f32_e32 v225, 1.0, v225
	v_rcp_f32_e32 v222, v222
	v_rcp_f32_e32 v223, v223
	v_rcp_f32_e32 v224, v224
	v_rcp_f32_e32 v225, v225
	v_mul_f32_e32 v164, v164, v222
	v_mul_f32_e32 v165, v165, v223
	v_mul_f32_e32 v166, v166, v224
	v_mul_f32_e32 v167, v167, v225
	v_mul_f32_e32 v164, v164, v168
	v_mul_f32_e32 v165, v165, v169
	v_mul_f32_e32 v166, v166, v170
	v_mul_f32_e32 v167, v167, v171
	v_cvt_pk_bf16_f32 v164, v164, v165
	v_cvt_pk_bf16_f32 v165, v166, v167
	v_add_u32_e32 v181, 0x18c000, v155
	global_store_dwordx2 v181, v[164:165], s[0:1] offset:32
	v_mov_b32_dpp v132, v48 row_shr:1 row_mask:0xf bank_mask:0xf
	v_mov_b32_dpp v133, v49 row_shr:1 row_mask:0xf bank_mask:0xf
	v_mov_b32_dpp v134, v50 row_shr:1 row_mask:0xf bank_mask:0xf
	v_mov_b32_dpp v135, v51 row_shr:1 row_mask:0xf bank_mask:0xf
	v_mov_b32_dpp v156, v48 row_shr:2 row_mask:0xf bank_mask:0xf
	v_mov_b32_dpp v157, v49 row_shr:2 row_mask:0xf bank_mask:0xf
	v_mov_b32_dpp v158, v50 row_shr:2 row_mask:0xf bank_mask:0xf
	v_mov_b32_dpp v159, v51 row_shr:2 row_mask:0xf bank_mask:0xf
	v_mov_b32_dpp v136, v32 row_shr:1 row_mask:0xf bank_mask:0xf
	v_mov_b32_dpp v137, v33 row_shr:1 row_mask:0xf bank_mask:0xf
	v_mov_b32_dpp v138, v34 row_shr:1 row_mask:0xf bank_mask:0xf
	v_mov_b32_dpp v139, v35 row_shr:1 row_mask:0xf bank_mask:0xf
; #define LAS __attribute__((address_space(3)))
; __device__ __forceinline__ float dpp_ror1(float v) { return __int_as_float(__builtin_amdgcn_update_dpp(0, __float_as_int(v), 0x121, 0xf, 0xf, false)); }
; __device__ __forceinline__ float dpp_ror2(float v) { return __int_as_float(__builtin_amdgcn_update_dpp(0, __float_as_int(v), 0x122, 0xf, 0xf, false)); }
; #define PG8_BAR __builtin_amdgcn_s_barrier()
;     __device__ __forceinline__ void operator()(f32x4 (&acc)[2][2][4][2], const Unit& u, int wr, int wc, int fr, int fq) const {
;     ...
;                     for (int e = 0; e < 4; ++e) { q1[bj][e] = dpp_ror1(acc[ai][bj][0][n][e]); q2[bj][e] = dpp_ror2(acc[ai][bj][0][n][e]); }
; #pragma unroll
;                 for (int m = 1; m < 4; ++m) conv_rows(acc[ai][0][m][n], acc[ai][1][m][n], q1, q2, cp, act + (size_t)(rowt + ai * HALF + m * 16) * FF + jcol, m < 3);
;             }
;         }
;         asm volatile("s_waitcnt lgkmcnt(0)" ::: "memory"); PG8_BAR; PG8_BAR; asm volatile("" ::: "memory");
; #pragma unroll
;         for (int n = 0; n < 2; ++n) {
;             const int jcol = u.pn * HALF + cl0 + n * 16; const LAS float* cp = myc + 16 * n + 4 * fq;
; #pragma unroll
;             for (int ai = 0; ai < 2; ++ai) {
;                 const bool has_prev = !(ai == 0 && wr == 0);
;                 const int slot = (wr == 1) ? (ai * 2) : ((ai - 1) * 2 + 1);
;                 f32x4 q1[2], q2[2];
; #pragma unroll
;                 for (int bj = 0; bj < 2; ++bj) {
;                     f32x4 e0 = (f32x4){0.f, 0.f, 0.f, 0.f}, e1 = (f32x4){0.f, 0.f, 0.f, 0.f};
;                     if (has_prev) { e0 = *(const LAS f32x4*)(ex + ((slot * 2 + 0) * 256 + bj * HALF + cl0 + n * 16)); e1 = *(const LAS f32x4*)(ex + ((slot * 2 + 1) * 256 + bj * HALF + cl0 + n * 16)); }
;                     q1[bj] = e1;
; #pragma unroll
;                     for (int e = 0; e < 4; ++e) q2[bj][e] = (fr == 1) ? e1[e] : e0[e];
	v_mov_b32_dpp v160, v32 row_shr:2 row_mask:0xf bank_mask:0xf
	v_mov_b32_dpp v161, v33 row_shr:2 row_mask:0xf bank_mask:0xf
	v_mov_b32_dpp v162, v34 row_shr:2 row_mask:0xf bank_mask:0xf
	v_mov_b32_dpp v163, v35 row_shr:2 row_mask:0xf bank_mask:0xf
	v_mov_b32_dpp v222, v48 row_ror:1 row_mask:0xf bank_mask:0xf
	v_mov_b32_dpp v223, v49 row_ror:1 row_mask:0xf bank_mask:0xf
	v_mov_b32_dpp v224, v50 row_ror:1 row_mask:0xf bank_mask:0xf
	v_mov_b32_dpp v225, v51 row_ror:1 row_mask:0xf bank_mask:0xf
	v_mov_b32_dpp v230, v48 row_ror:2 row_mask:0xf bank_mask:0xf
	v_mov_b32_dpp v231, v49 row_ror:2 row_mask:0xf bank_mask:0xf
	v_mov_b32_dpp v232, v50 row_ror:2 row_mask:0xf bank_mask:0xf
	v_mov_b32_dpp v233, v51 row_ror:2 row_mask:0xf bank_mask:0xf
	v_mov_b32_dpp v226, v32 row_ror:1 row_mask:0xf bank_mask:0xf
	v_mov_b32_dpp v227, v33 row_ror:1 row_mask:0xf bank_mask:0xf
	v_mov_b32_dpp v228, v34 row_ror:1 row_mask:0xf bank_mask:0xf
	v_mov_b32_dpp v229, v35 row_ror:1 row_mask:0xf bank_mask:0xf
	v_mov_b32_dpp v108, v32 row_ror:2 row_mask:0xf bank_mask:0xf
	v_mov_b32_dpp v109, v33 row_ror:2 row_mask:0xf bank_mask:0xf
	v_mov_b32_dpp v110, v34 row_ror:2 row_mask:0xf bank_mask:0xf
	v_mov_b32_dpp v111, v35 row_ror:2 row_mask:0xf bank_mask:0xf
	v_pk_fma_f32 v[164:165], v[188:189], v[156:157], v[214:215]
	v_pk_fma_f32 v[166:167], v[190:191], v[158:159], v[216:217]
	v_pk_fma_f32 v[164:165], v[196:197], v[132:133], v[164:165]
	v_pk_fma_f32 v[166:167], v[198:199], v[134:135], v[166:167]
	v_pk_fma_f32 v[164:165], v[48:49], v[204:205], v[164:165]
	v_pk_fma_f32 v[166:167], v[50:51], v[206:207], v[166:167]
	v_pk_fma_f32 v[168:169], v[192:193], v[160:161], v[218:219]
	v_pk_fma_f32 v[170:171], v[194:195], v[162:163], v[220:221]
	v_pk_fma_f32 v[168:169], v[200:201], v[136:137], v[168:169]
	v_pk_fma_f32 v[170:171], v[202:203], v[138:139], v[170:171]
	v_pk_fma_f32 v[168:169], v[32:33], v[210:211], v[168:169]
	v_pk_fma_f32 v[170:171], v[34:35], v[212:213], v[170:171]
	v_mul_f32_e32 v132, 0xbfb8aa3b, v164
	v_mul_f32_e32 v133, 0xbfb8aa3b, v165
	v_mul_f32_e32 v134, 0xbfb8aa3b, v166
	v_mul_f32_e32 v135, 0xbfb8aa3b, v167
	v_exp_f32_e32 v132, v132
	v_exp_f32_e32 v133, v133
	v_exp_f32_e32 v134, v134
	v_exp_f32_e32 v135, v135
	v_add_f32_e32 v132, 1.0, v132
	v_add_f32_e32 v133, 1.0, v133
	v_add_f32_e32 v134, 1.0, v134
	v_add_f32_e32 v135, 1.0, v135
	v_rcp_f32_e32 v132, v132
	v_rcp_f32_e32 v133, v133
	v_rcp_f32_e32 v134, v134
	v_rcp_f32_e32 v135, v135
	v_mul_f32_e32 v164, v164, v132
	v_mul_f32_e32 v165, v165, v133
	v_mul_f32_e32 v166, v166, v134
	v_mul_f32_e32 v167, v167, v135
	v_mul_f32_e32 v164, v164, v168
	v_mul_f32_e32 v165, v165, v169
	v_mul_f32_e32 v166, v166, v170
	v_mul_f32_e32 v167, v167, v171
	v_cvt_pk_bf16_f32 v164, v164, v165
	v_cvt_pk_bf16_f32 v165, v166, v167
	v_add_u32_e32 v181, 0x1b8000, v155
	global_store_dwordx2 v181, v[164:165], s[0:1] offset:32
	v_mov_b32_dpp v222, v8 row_shr:1 row_mask:0xf bank_mask:0xf
	v_mov_b32_dpp v223, v9 row_shr:1 row_mask:0xf bank_mask:0xf
	v_mov_b32_dpp v224, v10 row_shr:1 row_mask:0xf bank_mask:0xf
	v_mov_b32_dpp v225, v11 row_shr:1 row_mask:0xf bank_mask:0xf
	v_mov_b32_dpp v230, v8 row_shr:2 row_mask:0xf bank_mask:0xf
	v_mov_b32_dpp v231, v9 row_shr:2 row_mask:0xf bank_mask:0xf
	v_mov_b32_dpp v232, v10 row_shr:2 row_mask:0xf bank_mask:0xf
	v_mov_b32_dpp v233, v11 row_shr:2 row_mask:0xf bank_mask:0xf
	v_mov_b32_dpp v226, v0 row_shr:1 row_mask:0xf bank_mask:0xf
	v_mov_b32_dpp v227, v1 row_shr:1 row_mask:0xf bank_mask:0xf
	v_mov_b32_dpp v228, v2 row_shr:1 row_mask:0xf bank_mask:0xf
	v_mov_b32_dpp v229, v3 row_shr:1 row_mask:0xf bank_mask:0xf
	v_mov_b32_dpp v108, v0 row_shr:2 row_mask:0xf bank_mask:0xf
	v_mov_b32_dpp v109, v1 row_shr:2 row_mask:0xf bank_mask:0xf
	v_mov_b32_dpp v110, v2 row_shr:2 row_mask:0xf bank_mask:0xf
	v_mov_b32_dpp v111, v3 row_shr:2 row_mask:0xf bank_mask:0xf
	v_pk_fma_f32 v[164:165], v[188:189], v[230:231], v[214:215]
	v_pk_fma_f32 v[166:167], v[190:191], v[232:233], v[216:217]
	v_pk_fma_f32 v[164:165], v[196:197], v[222:223], v[164:165]
	v_pk_fma_f32 v[166:167], v[198:199], v[224:225], v[166:167]
	v_pk_fma_f32 v[164:165], v[8:9], v[204:205], v[164:165]
	v_pk_fma_f32 v[166:167], v[10:11], v[206:207], v[166:167]
	v_pk_fma_f32 v[168:169], v[192:193], v[108:109], v[218:219]
	v_pk_fma_f32 v[170:171], v[194:195], v[110:111], v[220:221]
	v_pk_fma_f32 v[168:169], v[200:201], v[226:227], v[168:169]
	v_pk_fma_f32 v[170:171], v[202:203], v[228:229], v[170:171]
	v_pk_fma_f32 v[168:169], v[0:1], v[210:211], v[168:169]
	v_pk_fma_f32 v[170:171], v[2:3], v[212:213], v[170:171]
	v_mul_f32_e32 v222, 0xbfb8aa3b, v164
	v_mul_f32_e32 v223, 0xbfb8aa3b, v165
	v_mul_f32_e32 v224, 0xbfb8aa3b, v166
	v_mul_f32_e32 v225, 0xbfb8aa3b, v167
	v_exp_f32_e32 v222, v222
	v_exp_f32_e32 v223, v223
	v_exp_f32_e32 v224, v224
	v_exp_f32_e32 v225, v225
	v_add_f32_e32 v222, 1.0, v222
	v_add_f32_e32 v223, 1.0, v223
	v_add_f32_e32 v224, 1.0, v224
	v_add_f32_e32 v225, 1.0, v225
	v_rcp_f32_e32 v222, v222
	v_rcp_f32_e32 v223, v223
	v_rcp_f32_e32 v224, v224
	v_rcp_f32_e32 v225, v225
	v_mul_f32_e32 v164, v164, v222
	v_mul_f32_e32 v165, v165, v223
	v_mul_f32_e32 v166, v166, v224
	v_mul_f32_e32 v167, v167, v225
	v_mul_f32_e32 v164, v164, v168
	v_mul_f32_e32 v165, v165, v169
	v_mul_f32_e32 v166, v166, v170
	v_mul_f32_e32 v167, v167, v171
	v_cvt_pk_bf16_f32 v164, v164, v165
	v_cvt_pk_bf16_f32 v165, v166, v167
	v_add_u32_e32 v181, 0x1e4000, v155
	global_store_dwordx2 v181, v[164:165], s[0:1] offset:32
	s_waitcnt lgkmcnt(0)
	s_barrier
	s_barrier
	s_cmp_lg_u32 s22, 0
	s_cselect_b32 s14, 0, 0xfffff800
	v_lshl_add_u32 v180, v154, 2, s66
	v_add_u32_e32 v180, s14, v180
	ds_read_b128 v[188:191], v153
	ds_read_b128 v[192:195], v153 offset:128
	ds_read_b128 v[196:199], v153 offset:256
	ds_read_b128 v[200:203], v153 offset:384
	ds_read_b128 v[204:207], v153 offset:512
	ds_read_b128 v[210:213], v153 offset:640
	ds_read_b128 v[214:217], v153 offset:768
	ds_read_b128 v[218:221], v153 offset:896
	s_cmp_lg_u32 s22, 0
	s_cbranch_scc1 .Lp6_b_00_prev
	v_mov_b32_e32 v222, 0
	v_mov_b32_e32 v223, 0
	v_mov_b32_e32 v224, 0
	v_mov_b32_e32 v225, 0
	v_mov_b32_e32 v226, 0
	v_mov_b32_e32 v227, 0
	v_mov_b32_e32 v228, 0
	v_mov_b32_e32 v229, 0
	v_mov_b32_e32 v230, 0
	v_mov_b32_e32 v231, 0
	v_mov_b32_e32 v232, 0
	v_mov_b32_e32 v233, 0
	v_mov_b32_e32 v108, 0
	v_mov_b32_e32 v109, 0
	v_mov_b32_e32 v110, 0
	v_mov_b32_e32 v111, 0
	s_branch .Lp6_b_00_go
; #define LAS __attribute__((address_space(3)))
;     __device__ __forceinline__ void operator()(f32x4 (&acc)[2][2][4][2], const Unit& u, int wr, int wc, int fr, int fq) const {
;     ...
; #pragma unroll
;         for (int n = 0; n < 2; ++n) {
;             const int jcol = u.pn * HALF + cl0 + n * 16; const LAS float* cp = myc + 16 * n + 4 * fq;
; #pragma unroll
;             for (int ai = 0; ai < 2; ++ai) {
;                 const bool has_prev = !(ai == 0 && wr == 0);
;                 const int slot = (wr == 1) ? (ai * 2) : ((ai - 1) * 2 + 1);
;                 f32x4 q1[2], q2[2];
; #pragma unroll
;                 for (int bj = 0; bj < 2; ++bj) {
;                     f32x4 e0 = (f32x4){0.f, 0.f, 0.f, 0.f}, e1 = (f32x4){0.f, 0.f, 0.f, 0.f};
;                     if (has_prev) { e0 = *(const LAS f32x4*)(ex + ((slot * 2 + 0) * 256 + bj * HALF + cl0 + n * 16)); e1 = *(const LAS f32x4*)(ex + ((slot * 2 + 1) * 256 + bj * HALF + cl0 + n * 16)); }
;                     q1[bj] = e1;
; #pragma unroll
;                     for (int e = 0; e < 4; ++e) q2[bj][e] = (fr == 1) ? e1[e] : e0[e];
;                 }
;                 conv_rows(acc[ai][0][0][n], acc[ai][1][0][n], q1, q2, cp, act + (size_t)(rowt + ai * HALF) * FF + jcol, false);
;             }
.Lp6_b_00_prev:
	ds_read_b128 v[132:135], v180 offset:0
	ds_read_b128 v[136:139], v180 offset:512
	ds_read_b128 v[222:225], v180 offset:1024
	ds_read_b128 v[226:229], v180 offset:1536
	s_waitcnt lgkmcnt(0)
	v_cndmask_b32_e64 v230, v132, v222, s[42:43]
	v_cndmask_b32_e64 v231, v133, v223, s[42:43]
	v_cndmask_b32_e64 v232, v134, v224, s[42:43]
	v_cndmask_b32_e64 v233, v135, v225, s[42:43]
	v_cndmask_b32_e64 v108, v136, v226, s[42:43]
	v_cndmask_b32_e64 v109, v137, v227, s[42:43]
	v_cndmask_b32_e64 v110, v138, v228, s[42:43]
	v_cndmask_b32_e64 v111, v139, v229, s[42:43]
.Lp6_b_00_go:
	s_waitcnt lgkmcnt(0)
	v_mov_b32_dpp v222, v128 row_shr:1 row_mask:0xf bank_mask:0xf
	v_mov_b32_dpp v223, v129 row_shr:1 row_mask:0xf bank_mask:0xf
	v_mov_b32_dpp v224, v130 row_shr:1 row_mask:0xf bank_mask:0xf
	v_mov_b32_dpp v225, v131 row_shr:1 row_mask:0xf bank_mask:0xf
	v_mov_b32_dpp v230, v128 row_shr:2 row_mask:0xf bank_mask:0xf
	v_mov_b32_dpp v231, v129 row_shr:2 row_mask:0xf bank_mask:0xf
	v_mov_b32_dpp v232, v130 row_shr:2 row_mask:0xf bank_mask:0xf
	v_mov_b32_dpp v233, v131 row_shr:2 row_mask:0xf bank_mask:0xf
	v_mov_b32_dpp v226, v12 row_shr:1 row_mask:0xf bank_mask:0xf
	v_mov_b32_dpp v227, v13 row_shr:1 row_mask:0xf bank_mask:0xf
	v_mov_b32_dpp v228, v14 row_shr:1 row_mask:0xf bank_mask:0xf
	v_mov_b32_dpp v229, v15 row_shr:1 row_mask:0xf bank_mask:0xf
	v_mov_b32_dpp v108, v12 row_shr:2 row_mask:0xf bank_mask:0xf
	v_mov_b32_dpp v109, v13 row_shr:2 row_mask:0xf bank_mask:0xf
	v_mov_b32_dpp v110, v14 row_shr:2 row_mask:0xf bank_mask:0xf
	v_mov_b32_dpp v111, v15 row_shr:2 row_mask:0xf bank_mask:0xf
	v_pk_fma_f32 v[164:165], v[188:189], v[230:231], v[214:215]
	v_pk_fma_f32 v[166:167], v[190:191], v[232:233], v[216:217]
	v_pk_fma_f32 v[164:165], v[196:197], v[222:223], v[164:165]
	v_pk_fma_f32 v[166:167], v[198:199], v[224:225], v[166:167]
	v_pk_fma_f32 v[164:165], v[128:129], v[204:205], v[164:165]
	v_pk_fma_f32 v[166:167], v[130:131], v[206:207], v[166:167]
	v_pk_fma_f32 v[168:169], v[192:193], v[108:109], v[218:219]
	v_pk_fma_f32 v[170:171], v[194:195], v[110:111], v[220:221]
	v_pk_fma_f32 v[168:169], v[200:201], v[226:227], v[168:169]
	v_pk_fma_f32 v[170:171], v[202:203], v[228:229], v[170:171]
	v_pk_fma_f32 v[168:169], v[12:13], v[210:211], v[168:169]
	v_pk_fma_f32 v[170:171], v[14:15], v[212:213], v[170:171]
	v_mul_f32_e32 v222, 0xbfb8aa3b, v164
	v_mul_f32_e32 v223, 0xbfb8aa3b, v165
	v_mul_f32_e32 v224, 0xbfb8aa3b, v166
	v_mul_f32_e32 v225, 0xbfb8aa3b, v167
	v_exp_f32_e32 v222, v222
	v_exp_f32_e32 v223, v223
	v_exp_f32_e32 v224, v224
	v_exp_f32_e32 v225, v225
	v_add_f32_e32 v222, 1.0, v222
	v_add_f32_e32 v223, 1.0, v223
	v_add_f32_e32 v224, 1.0, v224
	v_add_f32_e32 v225, 1.0, v225
	v_rcp_f32_e32 v222, v222
	v_rcp_f32_e32 v223, v223
	v_rcp_f32_e32 v224, v224
	v_rcp_f32_e32 v225, v225
	v_mul_f32_e32 v164, v164, v222
	v_mul_f32_e32 v165, v165, v223
	v_mul_f32_e32 v166, v166, v224
	v_mul_f32_e32 v167, v167, v225
	v_mul_f32_e32 v164, v164, v168
	v_mul_f32_e32 v165, v165, v169
	v_mul_f32_e32 v166, v166, v170
	v_mul_f32_e32 v167, v167, v171
	v_cvt_pk_bf16_f32 v164, v164, v165
	v_cvt_pk_bf16_f32 v165, v166, v167
	global_store_dwordx2 v155, v[164:165], s[0:1]
	ds_read_b128 v[132:135], v180 offset:4096
	ds_read_b128 v[136:139], v180 offset:4608
	ds_read_b128 v[222:225], v180 offset:5120
	ds_read_b128 v[226:229], v180 offset:5632
	s_waitcnt lgkmcnt(0)
	v_cndmask_b32_e64 v230, v132, v222, s[42:43]
	v_cndmask_b32_e64 v231, v133, v223, s[42:43]
	v_cndmask_b32_e64 v232, v134, v224, s[42:43]
	v_cndmask_b32_e64 v233, v135, v225, s[42:43]
	v_cndmask_b32_e64 v108, v136, v226, s[42:43]
	v_cndmask_b32_e64 v109, v137, v227, s[42:43]
	v_cndmask_b32_e64 v110, v138, v228, s[42:43]
	v_cndmask_b32_e64 v111, v139, v229, s[42:43]
	v_mov_b32_dpp v222, v76 row_shr:1 row_mask:0xf bank_mask:0xf
	v_mov_b32_dpp v223, v77 row_shr:1 row_mask:0xf bank_mask:0xf
	v_mov_b32_dpp v224, v78 row_shr:1 row_mask:0xf bank_mask:0xf
	v_mov_b32_dpp v225, v79 row_shr:1 row_mask:0xf bank_mask:0xf
	v_mov_b32_dpp v230, v76 row_shr:2 row_mask:0xf bank_mask:0xf
	v_mov_b32_dpp v231, v77 row_shr:2 row_mask:0xf bank_mask:0xf
	v_mov_b32_dpp v232, v78 row_shr:2 row_mask:0xf bank_mask:0xf
	v_mov_b32_dpp v233, v79 row_shr:2 row_mask:0xf bank_mask:0xf
	v_mov_b32_dpp v226, v60 row_shr:1 row_mask:0xf bank_mask:0xf
	v_mov_b32_dpp v227, v61 row_shr:1 row_mask:0xf bank_mask:0xf
	v_mov_b32_dpp v228, v62 row_shr:1 row_mask:0xf bank_mask:0xf
	v_mov_b32_dpp v229, v63 row_shr:1 row_mask:0xf bank_mask:0xf
	v_mov_b32_dpp v108, v60 row_shr:2 row_mask:0xf bank_mask:0xf
	v_mov_b32_dpp v109, v61 row_shr:2 row_mask:0xf bank_mask:0xf
	v_mov_b32_dpp v110, v62 row_shr:2 row_mask:0xf bank_mask:0xf
	v_mov_b32_dpp v111, v63 row_shr:2 row_mask:0xf bank_mask:0xf
	v_pk_fma_f32 v[164:165], v[188:189], v[230:231], v[214:215]
	v_pk_fma_f32 v[166:167], v[190:191], v[232:233], v[216:217]
	v_pk_fma_f32 v[164:165], v[196:197], v[222:223], v[164:165]
	v_pk_fma_f32 v[166:167], v[198:199], v[224:225], v[166:167]
	v_pk_fma_f32 v[164:165], v[76:77], v[204:205], v[164:165]
	v_pk_fma_f32 v[166:167], v[78:79], v[206:207], v[166:167]
	v_pk_fma_f32 v[168:169], v[192:193], v[108:109], v[218:219]
	v_pk_fma_f32 v[170:171], v[194:195], v[110:111], v[220:221]
	v_pk_fma_f32 v[168:169], v[200:201], v[226:227], v[168:169]
	v_pk_fma_f32 v[170:171], v[202:203], v[228:229], v[170:171]
	v_pk_fma_f32 v[168:169], v[60:61], v[210:211], v[168:169]
	v_pk_fma_f32 v[170:171], v[62:63], v[212:213], v[170:171]
	v_mul_f32_e32 v222, 0xbfb8aa3b, v164
	v_mul_f32_e32 v223, 0xbfb8aa3b, v165
	v_mul_f32_e32 v224, 0xbfb8aa3b, v166
	v_mul_f32_e32 v225, 0xbfb8aa3b, v167
	v_exp_f32_e32 v222, v222
	v_exp_f32_e32 v223, v223
	v_exp_f32_e32 v224, v224
	v_exp_f32_e32 v225, v225
	v_add_f32_e32 v222, 1.0, v222
	v_add_f32_e32 v223, 1.0, v223
	v_add_f32_e32 v224, 1.0, v224
	v_add_f32_e32 v225, 1.0, v225
	v_rcp_f32_e32 v222, v222
	v_rcp_f32_e32 v223, v223
	v_rcp_f32_e32 v224, v224
	v_rcp_f32_e32 v225, v225
	v_mul_f32_e32 v164, v164, v222
	v_mul_f32_e32 v165, v165, v223
	v_mul_f32_e32 v166, v166, v224
	v_mul_f32_e32 v167, v167, v225
	v_mul_f32_e32 v164, v164, v168
	v_mul_f32_e32 v165, v165, v169
	v_mul_f32_e32 v166, v166, v170
	v_mul_f32_e32 v167, v167, v171
	v_cvt_pk_bf16_f32 v164, v164, v165
	v_cvt_pk_bf16_f32 v165, v166, v167
	v_add_u32_e32 v181, 0x160000, v155
	global_store_dwordx2 v181, v[164:165], s[0:1]
	ds_read_b128 v[188:191], v153 offset:64
	ds_read_b128 v[192:195], v153 offset:192
	ds_read_b128 v[196:199], v153 offset:320
	ds_read_b128 v[200:203], v153 offset:448
	ds_read_b128 v[204:207], v153 offset:576
	ds_read_b128 v[210:213], v153 offset:704
	ds_read_b128 v[214:217], v153 offset:832
	ds_read_b128 v[218:221], v153 offset:960
	s_cmp_lg_u32 s22, 0
	s_cbranch_scc1 .Lp6_b_10_prev
; #define LAS __attribute__((address_space(3)))
; template <class Epi, bool KS0 = false>
; __device__ __forceinline__ void gemm_phase(const int WID, LAS unsigned char* lds, const Gemm g, const StaticOrder& S, const Epi& E) {
;     ...
;         cur = nxt; cA = nA; cB = nB; ++ui;
;     __device__ __forceinline__ void operator()(f32x4 (&acc)[2][2][4][2], const Unit& u, int wr, int wc, int fr, int fq) const {
;     ...
;             const int jcol = u.pn * HALF + cl0 + n * 16; const LAS float* cp = myc + 16 * n + 4 * fq;
; #pragma unroll
;             for (int ai = 0; ai < 2; ++ai) {
;                 const bool has_prev = !(ai == 0 && wr == 0);
;                 const int slot = (wr == 1) ? (ai * 2) : ((ai - 1) * 2 + 1);
;                 f32x4 q1[2], q2[2];
; #pragma unroll
;                 for (int bj = 0; bj < 2; ++bj) {
;                     f32x4 e0 = (f32x4){0.f, 0.f, 0.f, 0.f}, e1 = (f32x4){0.f, 0.f, 0.f, 0.f};
;                     if (has_prev) { e0 = *(const LAS f32x4*)(ex + ((slot * 2 + 0) * 256 + bj * HALF + cl0 + n * 16)); e1 = *(const LAS f32x4*)(ex + ((slot * 2 + 1) * 256 + bj * HALF + cl0 + n * 16)); }
;                     q1[bj] = e1;
; #pragma unroll
;                     for (int e = 0; e < 4; ++e) q2[bj][e] = (fr == 1) ? e1[e] : e0[e];
;                 }
;                 conv_rows(acc[ai][0][0][n], acc[ai][1][0][n], q1, q2, cp, act + (size_t)(rowt + ai * HALF) * FF + jcol, false);
;             }
;         }
	v_mov_b32_e32 v222, 0
	v_mov_b32_e32 v223, 0
	v_mov_b32_e32 v224, 0
	v_mov_b32_e32 v225, 0
	v_mov_b32_e32 v226, 0
	v_mov_b32_e32 v227, 0
	v_mov_b32_e32 v228, 0
	v_mov_b32_e32 v229, 0
	v_mov_b32_e32 v230, 0
	v_mov_b32_e32 v231, 0
	v_mov_b32_e32 v232, 0
	v_mov_b32_e32 v233, 0
	v_mov_b32_e32 v108, 0
	v_mov_b32_e32 v109, 0
	v_mov_b32_e32 v110, 0
	v_mov_b32_e32 v111, 0
	s_branch .Lp6_b_10_go
.Lp6_b_10_prev:
	ds_read_b128 v[132:135], v180 offset:64
	ds_read_b128 v[136:139], v180 offset:576
	ds_read_b128 v[222:225], v180 offset:1088
	ds_read_b128 v[226:229], v180 offset:1600
	s_waitcnt lgkmcnt(0)
	v_cndmask_b32_e64 v230, v132, v222, s[42:43]
	v_cndmask_b32_e64 v231, v133, v223, s[42:43]
	v_cndmask_b32_e64 v232, v134, v224, s[42:43]
	v_cndmask_b32_e64 v233, v135, v225, s[42:43]
	v_cndmask_b32_e64 v108, v136, v226, s[42:43]
	v_cndmask_b32_e64 v109, v137, v227, s[42:43]
	v_cndmask_b32_e64 v110, v138, v228, s[42:43]
	v_cndmask_b32_e64 v111, v139, v229, s[42:43]
.Lp6_b_10_go:
	s_waitcnt lgkmcnt(0)
	v_mov_b32_dpp v222, v124 row_shr:1 row_mask:0xf bank_mask:0xf
	v_mov_b32_dpp v223, v125 row_shr:1 row_mask:0xf bank_mask:0xf
	v_mov_b32_dpp v224, v126 row_shr:1 row_mask:0xf bank_mask:0xf
	v_mov_b32_dpp v225, v127 row_shr:1 row_mask:0xf bank_mask:0xf
	v_mov_b32_dpp v230, v124 row_shr:2 row_mask:0xf bank_mask:0xf
	v_mov_b32_dpp v231, v125 row_shr:2 row_mask:0xf bank_mask:0xf
	v_mov_b32_dpp v232, v126 row_shr:2 row_mask:0xf bank_mask:0xf
	v_mov_b32_dpp v233, v127 row_shr:2 row_mask:0xf bank_mask:0xf
	v_mov_b32_dpp v226, v120 row_shr:1 row_mask:0xf bank_mask:0xf
	v_mov_b32_dpp v227, v121 row_shr:1 row_mask:0xf bank_mask:0xf
	v_mov_b32_dpp v228, v122 row_shr:1 row_mask:0xf bank_mask:0xf
	v_mov_b32_dpp v229, v123 row_shr:1 row_mask:0xf bank_mask:0xf
	v_mov_b32_dpp v108, v120 row_shr:2 row_mask:0xf bank_mask:0xf
	v_mov_b32_dpp v109, v121 row_shr:2 row_mask:0xf bank_mask:0xf
	v_mov_b32_dpp v110, v122 row_shr:2 row_mask:0xf bank_mask:0xf
	v_mov_b32_dpp v111, v123 row_shr:2 row_mask:0xf bank_mask:0xf
	v_pk_fma_f32 v[164:165], v[188:189], v[230:231], v[214:215]
	v_pk_fma_f32 v[166:167], v[190:191], v[232:233], v[216:217]
	v_pk_fma_f32 v[164:165], v[196:197], v[222:223], v[164:165]
	v_pk_fma_f32 v[166:167], v[198:199], v[224:225], v[166:167]
	v_pk_fma_f32 v[164:165], v[124:125], v[204:205], v[164:165]
	v_pk_fma_f32 v[166:167], v[126:127], v[206:207], v[166:167]
	v_pk_fma_f32 v[168:169], v[192:193], v[108:109], v[218:219]
	v_pk_fma_f32 v[170:171], v[194:195], v[110:111], v[220:221]
	v_pk_fma_f32 v[168:169], v[200:201], v[226:227], v[168:169]
	v_pk_fma_f32 v[170:171], v[202:203], v[228:229], v[170:171]
	v_pk_fma_f32 v[168:169], v[120:121], v[210:211], v[168:169]
	v_pk_fma_f32 v[170:171], v[122:123], v[212:213], v[170:171]
	v_mul_f32_e32 v222, 0xbfb8aa3b, v164
	v_mul_f32_e32 v223, 0xbfb8aa3b, v165
	v_mul_f32_e32 v224, 0xbfb8aa3b, v166
	v_mul_f32_e32 v225, 0xbfb8aa3b, v167
	v_exp_f32_e32 v222, v222
	v_exp_f32_e32 v223, v223
	v_exp_f32_e32 v224, v224
	v_exp_f32_e32 v225, v225
	v_add_f32_e32 v222, 1.0, v222
	v_add_f32_e32 v223, 1.0, v223
	v_add_f32_e32 v224, 1.0, v224
	v_add_f32_e32 v225, 1.0, v225
	v_rcp_f32_e32 v222, v222
	v_rcp_f32_e32 v223, v223
	v_rcp_f32_e32 v224, v224
	v_rcp_f32_e32 v225, v225
	v_mul_f32_e32 v164, v164, v222
	v_mul_f32_e32 v165, v165, v223
	v_mul_f32_e32 v166, v166, v224
	v_mul_f32_e32 v167, v167, v225
	v_mul_f32_e32 v164, v164, v168
	v_mul_f32_e32 v165, v165, v169
	v_mul_f32_e32 v166, v166, v170
	v_mul_f32_e32 v167, v167, v171
	v_cvt_pk_bf16_f32 v164, v164, v165
	v_cvt_pk_bf16_f32 v165, v166, v167
	global_store_dwordx2 v155, v[164:165], s[0:1] offset:32
	ds_read_b128 v[132:135], v180 offset:4160
	ds_read_b128 v[136:139], v180 offset:4672
	ds_read_b128 v[222:225], v180 offset:5184
	ds_read_b128 v[226:229], v180 offset:5696
	s_waitcnt lgkmcnt(0)
	v_cndmask_b32_e64 v230, v132, v222, s[42:43]
	v_cndmask_b32_e64 v231, v133, v223, s[42:43]
	v_cndmask_b32_e64 v232, v134, v224, s[42:43]
	v_cndmask_b32_e64 v233, v135, v225, s[42:43]
	v_cndmask_b32_e64 v108, v136, v226, s[42:43]
	v_cndmask_b32_e64 v109, v137, v227, s[42:43]
	v_cndmask_b32_e64 v110, v138, v228, s[42:43]
	v_cndmask_b32_e64 v111, v139, v229, s[42:43]
	v_mov_b32_dpp v222, v72 row_shr:1 row_mask:0xf bank_mask:0xf
	v_mov_b32_dpp v223, v73 row_shr:1 row_mask:0xf bank_mask:0xf
	v_mov_b32_dpp v224, v74 row_shr:1 row_mask:0xf bank_mask:0xf
	v_mov_b32_dpp v225, v75 row_shr:1 row_mask:0xf bank_mask:0xf
	v_mov_b32_dpp v230, v72 row_shr:2 row_mask:0xf bank_mask:0xf
	v_mov_b32_dpp v231, v73 row_shr:2 row_mask:0xf bank_mask:0xf
	v_mov_b32_dpp v232, v74 row_shr:2 row_mask:0xf bank_mask:0xf
	v_mov_b32_dpp v233, v75 row_shr:2 row_mask:0xf bank_mask:0xf
	v_mov_b32_dpp v226, v56 row_shr:1 row_mask:0xf bank_mask:0xf
	v_mov_b32_dpp v227, v57 row_shr:1 row_mask:0xf bank_mask:0xf
	v_mov_b32_dpp v228, v58 row_shr:1 row_mask:0xf bank_mask:0xf
	v_mov_b32_dpp v229, v59 row_shr:1 row_mask:0xf bank_mask:0xf
	v_mov_b32_dpp v108, v56 row_shr:2 row_mask:0xf bank_mask:0xf
	v_mov_b32_dpp v109, v57 row_shr:2 row_mask:0xf bank_mask:0xf
	v_mov_b32_dpp v110, v58 row_shr:2 row_mask:0xf bank_mask:0xf
	v_mov_b32_dpp v111, v59 row_shr:2 row_mask:0xf bank_mask:0xf
	v_pk_fma_f32 v[164:165], v[188:189], v[230:231], v[214:215]
	v_pk_fma_f32 v[166:167], v[190:191], v[232:233], v[216:217]
	v_pk_fma_f32 v[164:165], v[196:197], v[222:223], v[164:165]
	v_pk_fma_f32 v[166:167], v[198:199], v[224:225], v[166:167]
	v_pk_fma_f32 v[164:165], v[72:73], v[204:205], v[164:165]
	v_pk_fma_f32 v[166:167], v[74:75], v[206:207], v[166:167]
	v_pk_fma_f32 v[168:169], v[192:193], v[108:109], v[218:219]
	v_pk_fma_f32 v[170:171], v[194:195], v[110:111], v[220:221]
	v_pk_fma_f32 v[168:169], v[200:201], v[226:227], v[168:169]
	v_pk_fma_f32 v[170:171], v[202:203], v[228:229], v[170:171]
	v_pk_fma_f32 v[168:169], v[56:57], v[210:211], v[168:169]
	v_pk_fma_f32 v[170:171], v[58:59], v[212:213], v[170:171]
	v_mul_f32_e32 v222, 0xbfb8aa3b, v164
	v_mul_f32_e32 v223, 0xbfb8aa3b, v165
	v_mul_f32_e32 v224, 0xbfb8aa3b, v166
	v_mul_f32_e32 v225, 0xbfb8aa3b, v167
	v_exp_f32_e32 v222, v222
	v_exp_f32_e32 v223, v223
	v_exp_f32_e32 v224, v224
	v_exp_f32_e32 v225, v225
	v_add_f32_e32 v222, 1.0, v222
	v_add_f32_e32 v223, 1.0, v223
	v_add_f32_e32 v224, 1.0, v224
	v_add_f32_e32 v225, 1.0, v225
	v_rcp_f32_e32 v222, v222
	v_rcp_f32_e32 v223, v223
	v_rcp_f32_e32 v224, v224
	v_rcp_f32_e32 v225, v225
	v_mul_f32_e32 v164, v164, v222
	v_mul_f32_e32 v165, v165, v223
	v_mul_f32_e32 v166, v166, v224
	v_mul_f32_e32 v167, v167, v225
	v_mul_f32_e32 v164, v164, v168
	v_mul_f32_e32 v165, v165, v169
	v_mul_f32_e32 v166, v166, v170
	v_mul_f32_e32 v167, v167, v171
	v_cvt_pk_bf16_f32 v164, v164, v165
	v_cvt_pk_bf16_f32 v165, v166, v167
	v_add_u32_e32 v181, 0x160000, v155
	global_store_dwordx2 v181, v[164:165], s[0:1] offset:32
	s_mov_b32 s8, s52
	s_mov_b32 s10, s54
	s_mov_b64 s[12:13], s[58:59]
	s_mov_b64 s[2:3], s[56:57]
	s_and_b64 vcc, exec, s[40:41]
	s_cbranch_vccnz .LBB0_812
	s_branch .LBB0_774
